# norm pipelines no longer wait on their newest stores; ssd_combine hand-written with two rows in flight; prep silu division via v_rcp_f32
# speedup vs baseline: 1.0136x; 1.0048x over previous
; DI int TID() { int t = threadIdx.x; asm volatile("" : "+v"(t)); return t; }
; DI u32 pack2(float a, float b) { return (u32)f2bf(a) | ((u32)f2bf(b) << 16); }
; DI void phase_norm(const Params& p, int l, int which, int bid, int nblk) {
;   const int lane = TID() & 63, w = TID() >> 6;
;   const float* g = (which ? p.in[I_G2] : p.in[I_G1]) + l * 1024;
;   const bool from_input = (which == 0 && l == 0);
;   for (int row = bid * 4 + w; row < ROWS; row += nblk * 4) {
;     const int b = row / TPB, pos = row % TPB;
;     if (which == 1 && l == 1 && pos < CTXL) continue;
;     const float* xr = xrow_ptr(p, from_input, b, pos);
;     const float* mod = WSP(const float, OFF_MOD) + (size_t)(l * 17 + (pos < CTXL ? 16 : b)) * 6144 + which * 3072;
;     float x[16];
; #pragma unroll
;     for (int hh = 0; hh < 2; ++hh) {
;       const float4 a = *(const float4*)(xr + hh * 512 + lane * 8);
;       const float4 c = *(const float4*)(xr + hh * 512 + lane * 8 + 4);
;       x[hh * 8 + 0] = a.x; x[hh * 8 + 1] = a.y; x[hh * 8 + 2] = a.z; x[hh * 8 + 3] = a.w;
;       x[hh * 8 + 4] = c.x; x[hh * 8 + 5] = c.y; x[hh * 8 + 6] = c.z; x[hh * 8 + 7] = c.w;
;     }
;     float ss = 0.f;
; #pragma unroll
;     for (int i = 0; i < 16; ++i) ss += x[i] * x[i];
;     ss = wave_sum(ss);
;     const float rs = rsqrtf(ss * (1.f / 1024.f) + EPSF);
; #pragma unroll
;     for (int hh = 0; hh < 2; ++hh) {
;       const int c0 = hh * 512 + lane * 8;
;       float y[8];
; #pragma unroll
;       for (int i = 0; i < 8; ++i) {
;         const float yn = x[hh * 8 + i] * rs * g[c0 + i];
;         y[i] = yn * (1.f + mod[1024 + c0 + i]) + mod[c0 + i];
;       }
;       uint4 o = {pack2(y[0], y[1]), pack2(y[2], y[3]), pack2(y[4], y[5]), pack2(y[6], y[7])};
;       *(uint4*)&WSP(u16, OFF_ACT)[(size_t)row * 1024 + c0] = o;
;     }
.Ln1_1_ptr:
	s_mul_i32 s46, s46, 0x6000
	s_add_u32 s36, s96, 0x1be04000
	s_addc_u32 s37, s97, 0
	s_add_u32 s36, s36, s46
	s_addc_u32 s37, s37, 0
	s_add_u32 s38, s36, 0x1000
	s_addc_u32 s39, s37, 0
	s_lshl_b32 s17, s44, 11
	s_add_u32 s50, s6, s17
	s_addc_u32 s51, s7, 0
	global_load_dwordx4 v[32:35], v4, s[30:31]
	global_load_dwordx4 v[36:39], v4, s[30:31] offset:1024
	global_load_dwordx4 v[40:43], v4, s[30:31] offset:2048
	global_load_dwordx4 v[44:47], v4, s[30:31] offset:3072
	global_load_dwordx4 v[64:67], v4, s[36:37]
	global_load_dwordx4 v[68:71], v4, s[36:37] offset:1024
	global_load_dwordx4 v[72:75], v4, s[36:37] offset:2048
	global_load_dwordx4 v[76:79], v4, s[36:37] offset:3072
	global_load_dwordx4 v[80:83], v4, s[38:39]
	global_load_dwordx4 v[84:87], v4, s[38:39] offset:1024
	global_load_dwordx4 v[88:91], v4, s[38:39] offset:2048
	global_load_dwordx4 v[92:95], v4, s[38:39] offset:3072
	s_mov_b32 s28, 1
	s_cmp_ge_u32 s28, s23
	s_addc_u32 s44, s28, 0
	s_cmp_ge_u32 s44, s25
	s_addc_u32 s44, s44, 0
	s_lshl_b32 s44, s44, 11
	s_add_i32 s44, s44, s19
	s_mul_hi_u32 s46, s44, 0x38e38e39
	s_lshr_b32 s46, s46, 9
	s_mul_i32 s16, s46, 0x900
	s_sub_u32 s16, s44, s16
	s_cmp_lt_u32 s16, 0x100
	s_cbranch_scc1 .Ln1_2_ctx
	s_lshl_b32 s17, s46, 11
	s_add_i32 s17, s17, s16
	s_add_i32 s17, s17, 0xffffff00
	s_lshl_b32 s17, s17, 12
	s_add_u32 s30, s66, s17
	s_addc_u32 s31, s67, 0
	s_add_i32 s46, s46, s65
	s_branch .Ln1_2_ptr

; DI u32 pack2(float a, float b) { return (u32)f2bf(a) | ((u32)f2bf(b) << 16); }
; DI void phase_norm(const Params& p, int l, int which, int bid, int nblk) {
;     ...
;     float x[16];
; #pragma unroll
;     for (int hh = 0; hh < 2; ++hh) {
;       const float4 a = *(const float4*)(xr + hh * 512 + lane * 8);
;       const float4 c = *(const float4*)(xr + hh * 512 + lane * 8 + 4);
;       x[hh * 8 + 0] = a.x; x[hh * 8 + 1] = a.y; x[hh * 8 + 2] = a.z; x[hh * 8 + 3] = a.w;
;       x[hh * 8 + 4] = c.x; x[hh * 8 + 5] = c.y; x[hh * 8 + 6] = c.z; x[hh * 8 + 7] = c.w;
;     }
;     float ss = 0.f;
; #pragma unroll
;     for (int i = 0; i < 16; ++i) ss += x[i] * x[i];
;     ss = wave_sum(ss);
;     const float rs = rsqrtf(ss * (1.f / 1024.f) + EPSF);
; #pragma unroll
;     for (int hh = 0; hh < 2; ++hh) {
;       const int c0 = hh * 512 + lane * 8;
;       float y[8];
; #pragma unroll
;       for (int i = 0; i < 8; ++i) {
;         const float yn = x[hh * 8 + i] * rs * g[c0 + i];
;         y[i] = yn * (1.f + mod[1024 + c0 + i]) + mod[c0 + i];
;       }
;       uint4 o = {pack2(y[0], y[1]), pack2(y[2], y[3]), pack2(y[4], y[5]), pack2(y[6], y[7])};
;       *(uint4*)&WSP(u16, OFF_ACT)[(size_t)row * 1024 + c0] = o;
;     }
.Ln1_top:
	s_waitcnt vmcnt(16)
	v_mul_f32_e32 v7, v32, v32
	v_fmac_f32_e32 v7, v33, v33
	v_fmac_f32_e32 v7, v34, v34
	v_fmac_f32_e32 v7, v35, v35
	v_fmac_f32_e32 v7, v36, v36
	v_fmac_f32_e32 v7, v37, v37
	v_fmac_f32_e32 v7, v38, v38
	v_fmac_f32_e32 v7, v39, v39
	v_fmac_f32_e32 v7, v40, v40
	v_fmac_f32_e32 v7, v41, v41
	v_fmac_f32_e32 v7, v42, v42
	v_fmac_f32_e32 v7, v43, v43
	v_fmac_f32_e32 v7, v44, v44
	v_fmac_f32_e32 v7, v45, v45
	v_fmac_f32_e32 v7, v46, v46
	v_fmac_f32_e32 v7, v47, v47
	s_nop 1
	v_add_f32_dpp v7, v7, v7 quad_perm:[1,0,3,2] row_mask:0xf bank_mask:0xf
	s_nop 1
	v_add_f32_dpp v7, v7, v7 quad_perm:[2,3,0,1] row_mask:0xf bank_mask:0xf
	s_nop 1
	v_add_f32_dpp v7, v7, v7 row_half_mirror row_mask:0xf bank_mask:0xf
	s_nop 1
	v_add_f32_dpp v7, v7, v7 row_mirror row_mask:0xf bank_mask:0xf
	s_nop 1
	ds_bpermute_b32 v8, v5, v7
	s_waitcnt lgkmcnt(0)
	v_add_f32_e32 v7, v7, v8
	ds_bpermute_b32 v8, v6, v7
	s_waitcnt lgkmcnt(0)
	v_add_f32_e32 v7, v7, v8
	v_mov_b32_e32 v8, 0x358637bd
	v_fmac_f32_e32 v8, 0x3a800000, v7
	v_rsq_f32_e32 v8, v8
	s_nop 0
	v_mul_f32_e32 v32, v32, v8
	v_mul_f32_e32 v33, v33, v8
	v_mul_f32_e32 v34, v34, v8
	v_mul_f32_e32 v35, v35, v8
	v_mul_f32_e32 v36, v36, v8
	v_mul_f32_e32 v37, v37, v8
	v_mul_f32_e32 v38, v38, v8
	v_mul_f32_e32 v39, v39, v8
	v_mul_f32_e32 v40, v40, v8
	v_mul_f32_e32 v41, v41, v8
	v_mul_f32_e32 v42, v42, v8
	v_mul_f32_e32 v43, v43, v8
	v_mul_f32_e32 v44, v44, v8
	v_mul_f32_e32 v45, v45, v8
	v_mul_f32_e32 v46, v46, v8
	v_mul_f32_e32 v47, v47, v8
	v_mul_f32_e32 v32, v32, v16
	v_mul_f32_e32 v33, v33, v17
	v_mul_f32_e32 v34, v34, v18
	v_mul_f32_e32 v35, v35, v19
	v_mul_f32_e32 v36, v36, v20
	v_mul_f32_e32 v37, v37, v21
	v_mul_f32_e32 v38, v38, v22
	v_mul_f32_e32 v39, v39, v23
	v_mul_f32_e32 v40, v40, v24
	v_mul_f32_e32 v41, v41, v25
	v_mul_f32_e32 v42, v42, v26
	v_mul_f32_e32 v43, v43, v27
	v_mul_f32_e32 v44, v44, v28
	v_mul_f32_e32 v45, v45, v29
	v_mul_f32_e32 v46, v46, v30
	v_mul_f32_e32 v47, v47, v31
	v_add_f32_e32 v80, 1.0, v80
	v_add_f32_e32 v81, 1.0, v81
	v_add_f32_e32 v82, 1.0, v82
	v_add_f32_e32 v83, 1.0, v83
	v_add_f32_e32 v84, 1.0, v84
	v_add_f32_e32 v85, 1.0, v85
	v_add_f32_e32 v86, 1.0, v86
	v_add_f32_e32 v87, 1.0, v87
	v_add_f32_e32 v88, 1.0, v88
	v_add_f32_e32 v89, 1.0, v89
	v_add_f32_e32 v90, 1.0, v90
	v_add_f32_e32 v91, 1.0, v91
	v_add_f32_e32 v92, 1.0, v92
	v_add_f32_e32 v93, 1.0, v93
	v_add_f32_e32 v94, 1.0, v94
	v_add_f32_e32 v95, 1.0, v95
	v_fma_f32 v32, v32, v80, v64
	v_fma_f32 v33, v33, v81, v65
	v_fma_f32 v34, v34, v82, v66
	v_fma_f32 v35, v35, v83, v67
	v_fma_f32 v36, v36, v84, v68
	v_fma_f32 v37, v37, v85, v69
	v_fma_f32 v38, v38, v86, v70
	v_fma_f32 v39, v39, v87, v71
	v_fma_f32 v40, v40, v88, v72
	v_fma_f32 v41, v41, v89, v73
	v_fma_f32 v42, v42, v90, v74
	v_fma_f32 v43, v43, v91, v75
	v_fma_f32 v44, v44, v92, v76
	v_fma_f32 v45, v45, v93, v77
	v_fma_f32 v46, v46, v94, v78
	v_fma_f32 v47, v47, v95, v79
	v_cvt_pk_bf16_f32 v32, v32, v33
	v_cvt_pk_bf16_f32 v33, v34, v35
	v_cvt_pk_bf16_f32 v34, v36, v37
	v_cvt_pk_bf16_f32 v35, v38, v39
	v_cvt_pk_bf16_f32 v36, v40, v41
	v_cvt_pk_bf16_f32 v37, v42, v43
	v_cvt_pk_bf16_f32 v38, v44, v45
	v_cvt_pk_bf16_f32 v39, v46, v47
	s_nop 0
	global_store_dwordx2 v9, v[32:33], s[50:51]
	global_store_dwordx2 v9, v[34:35], s[50:51] offset:512
	global_store_dwordx2 v9, v[36:37], s[50:51] offset:1024
	global_store_dwordx2 v9, v[38:39], s[50:51] offset:1536
	s_add_i32 s28, s27, 2
	s_cmp_lt_u32 s28, s26
	s_cselect_b32 s28, s28, 0
	s_cmp_ge_u32 s28, s23
	s_addc_u32 s44, s28, 0
	s_cmp_ge_u32 s44, s25
	s_addc_u32 s44, s44, 0
	s_lshl_b32 s44, s44, 11
	s_add_i32 s44, s44, s19
	s_mul_hi_u32 s46, s44, 0x38e38e39
	s_lshr_b32 s46, s46, 9
	s_mul_i32 s16, s46, 0x900
	s_sub_u32 s16, s44, s16
	s_cmp_lt_u32 s16, 0x100
	s_cbranch_scc1 .Ln1_3_ctx
	s_lshl_b32 s17, s46, 11
	s_add_i32 s17, s17, s16
	s_add_i32 s17, s17, 0xffffff00
	s_lshl_b32 s17, s17, 12
	s_add_u32 s30, s66, s17
	s_addc_u32 s31, s67, 0
	s_add_i32 s46, s46, s65
	s_branch .Ln1_3_ptr

; DI u32 pack2(float a, float b) { return (u32)f2bf(a) | ((u32)f2bf(b) << 16); }
; DI void phase_norm(const Params& p, int l, int which, int bid, int nblk) {
;     ...
;     float x[16];
; #pragma unroll
;     for (int hh = 0; hh < 2; ++hh) {
;       const float4 a = *(const float4*)(xr + hh * 512 + lane * 8);
;       const float4 c = *(const float4*)(xr + hh * 512 + lane * 8 + 4);
;       x[hh * 8 + 0] = a.x; x[hh * 8 + 1] = a.y; x[hh * 8 + 2] = a.z; x[hh * 8 + 3] = a.w;
;       x[hh * 8 + 4] = c.x; x[hh * 8 + 5] = c.y; x[hh * 8 + 6] = c.z; x[hh * 8 + 7] = c.w;
;     }
;     float ss = 0.f;
; #pragma unroll
;     for (int i = 0; i < 16; ++i) ss += x[i] * x[i];
;     ss = wave_sum(ss);
;     const float rs = rsqrtf(ss * (1.f / 1024.f) + EPSF);
; #pragma unroll
;     for (int hh = 0; hh < 2; ++hh) {
;       const int c0 = hh * 512 + lane * 8;
;       float y[8];
; #pragma unroll
;       for (int i = 0; i < 8; ++i) {
;         const float yn = x[hh * 8 + i] * rs * g[c0 + i];
;         y[i] = yn * (1.f + mod[1024 + c0 + i]) + mod[c0 + i];
;       }
;       uint4 o = {pack2(y[0], y[1]), pack2(y[2], y[3]), pack2(y[4], y[5]), pack2(y[6], y[7])};
;       *(uint4*)&WSP(u16, OFF_ACT)[(size_t)row * 1024 + c0] = o;
;     }
.Ln1_3_ptr:
	s_mul_i32 s46, s46, 0x6000
	s_add_u32 s36, s96, 0x1be04000
	s_addc_u32 s37, s97, 0
	s_add_u32 s36, s36, s46
	s_addc_u32 s37, s37, 0
	s_add_u32 s38, s36, 0x1000
	s_addc_u32 s39, s37, 0
	s_lshl_b32 s17, s44, 11
	s_add_u32 s50, s6, s17
	s_addc_u32 s51, s7, 0
	global_load_dwordx4 v[32:35], v4, s[30:31]
	global_load_dwordx4 v[36:39], v4, s[30:31] offset:1024
	global_load_dwordx4 v[40:43], v4, s[30:31] offset:2048
	global_load_dwordx4 v[44:47], v4, s[30:31] offset:3072
	global_load_dwordx4 v[64:67], v4, s[36:37]
	global_load_dwordx4 v[68:71], v4, s[36:37] offset:1024
	global_load_dwordx4 v[72:75], v4, s[36:37] offset:2048
	global_load_dwordx4 v[76:79], v4, s[36:37] offset:3072
	global_load_dwordx4 v[80:83], v4, s[38:39]
	global_load_dwordx4 v[84:87], v4, s[38:39] offset:1024
	global_load_dwordx4 v[88:91], v4, s[38:39] offset:2048
	global_load_dwordx4 v[92:95], v4, s[38:39] offset:3072
	s_waitcnt vmcnt(16)
	v_mul_f32_e32 v7, v48, v48
	v_fmac_f32_e32 v7, v49, v49
	v_fmac_f32_e32 v7, v50, v50
	v_fmac_f32_e32 v7, v51, v51
	v_fmac_f32_e32 v7, v52, v52
	v_fmac_f32_e32 v7, v53, v53
	v_fmac_f32_e32 v7, v54, v54
	v_fmac_f32_e32 v7, v55, v55
	v_fmac_f32_e32 v7, v56, v56
	v_fmac_f32_e32 v7, v57, v57
	v_fmac_f32_e32 v7, v58, v58
	v_fmac_f32_e32 v7, v59, v59
	v_fmac_f32_e32 v7, v60, v60
	v_fmac_f32_e32 v7, v61, v61
	v_fmac_f32_e32 v7, v62, v62
	v_fmac_f32_e32 v7, v63, v63
	s_nop 1
	v_add_f32_dpp v7, v7, v7 quad_perm:[1,0,3,2] row_mask:0xf bank_mask:0xf
	s_nop 1
	v_add_f32_dpp v7, v7, v7 quad_perm:[2,3,0,1] row_mask:0xf bank_mask:0xf
	s_nop 1
	v_add_f32_dpp v7, v7, v7 row_half_mirror row_mask:0xf bank_mask:0xf
	s_nop 1
	v_add_f32_dpp v7, v7, v7 row_mirror row_mask:0xf bank_mask:0xf
	s_nop 1
	ds_bpermute_b32 v8, v5, v7
	s_waitcnt lgkmcnt(0)
	v_add_f32_e32 v7, v7, v8
	ds_bpermute_b32 v8, v6, v7
	s_waitcnt lgkmcnt(0)
	v_add_f32_e32 v7, v7, v8
	v_mov_b32_e32 v8, 0x358637bd
	v_fmac_f32_e32 v8, 0x3a800000, v7
	v_rsq_f32_e32 v8, v8
	s_nop 0
	v_mul_f32_e32 v48, v48, v8
	v_mul_f32_e32 v49, v49, v8
	v_mul_f32_e32 v50, v50, v8
	v_mul_f32_e32 v51, v51, v8
	v_mul_f32_e32 v52, v52, v8
	v_mul_f32_e32 v53, v53, v8
	v_mul_f32_e32 v54, v54, v8
	v_mul_f32_e32 v55, v55, v8
	v_mul_f32_e32 v56, v56, v8
	v_mul_f32_e32 v57, v57, v8
	v_mul_f32_e32 v58, v58, v8
	v_mul_f32_e32 v59, v59, v8
	v_mul_f32_e32 v60, v60, v8
	v_mul_f32_e32 v61, v61, v8
	v_mul_f32_e32 v62, v62, v8
	v_mul_f32_e32 v63, v63, v8
	v_mul_f32_e32 v48, v48, v16
	v_mul_f32_e32 v49, v49, v17
	v_mul_f32_e32 v50, v50, v18
	v_mul_f32_e32 v51, v51, v19
	v_mul_f32_e32 v52, v52, v20
	v_mul_f32_e32 v53, v53, v21
	v_mul_f32_e32 v54, v54, v22
	v_mul_f32_e32 v55, v55, v23
	v_mul_f32_e32 v56, v56, v24
	v_mul_f32_e32 v57, v57, v25
	v_mul_f32_e32 v58, v58, v26
	v_mul_f32_e32 v59, v59, v27
	v_mul_f32_e32 v60, v60, v28
	v_mul_f32_e32 v61, v61, v29
	v_mul_f32_e32 v62, v62, v30
	v_mul_f32_e32 v63, v63, v31
	v_add_f32_e32 v112, 1.0, v112
	v_add_f32_e32 v113, 1.0, v113
	v_add_f32_e32 v114, 1.0, v114
	v_add_f32_e32 v115, 1.0, v115
	v_add_f32_e32 v116, 1.0, v116
	v_add_f32_e32 v117, 1.0, v117
	v_add_f32_e32 v118, 1.0, v118
	v_add_f32_e32 v119, 1.0, v119
	v_add_f32_e32 v120, 1.0, v120
	v_add_f32_e32 v121, 1.0, v121
	v_add_f32_e32 v122, 1.0, v122
	v_add_f32_e32 v123, 1.0, v123
	v_add_f32_e32 v124, 1.0, v124
	v_add_f32_e32 v125, 1.0, v125
	v_add_f32_e32 v126, 1.0, v126
	v_add_f32_e32 v127, 1.0, v127
	v_fma_f32 v48, v48, v112, v96
	v_fma_f32 v49, v49, v113, v97
	v_fma_f32 v50, v50, v114, v98
	v_fma_f32 v51, v51, v115, v99
	v_fma_f32 v52, v52, v116, v100
	v_fma_f32 v53, v53, v117, v101
	v_fma_f32 v54, v54, v118, v102
	v_fma_f32 v55, v55, v119, v103
	v_fma_f32 v56, v56, v120, v104
	v_fma_f32 v57, v57, v121, v105
	v_fma_f32 v58, v58, v122, v106
	v_fma_f32 v59, v59, v123, v107
	v_fma_f32 v60, v60, v124, v108
	v_fma_f32 v61, v61, v125, v109
	v_fma_f32 v62, v62, v126, v110
	v_fma_f32 v63, v63, v127, v111
	v_cvt_pk_bf16_f32 v48, v48, v49
	v_cvt_pk_bf16_f32 v49, v50, v51
	v_cvt_pk_bf16_f32 v50, v52, v53
	v_cvt_pk_bf16_f32 v51, v54, v55
	v_cvt_pk_bf16_f32 v52, v56, v57
	v_cvt_pk_bf16_f32 v53, v58, v59
	v_cvt_pk_bf16_f32 v54, v60, v61
	v_cvt_pk_bf16_f32 v55, v62, v63
	s_nop 0
	global_store_dwordx2 v9, v[48:49], s[56:57]
	global_store_dwordx2 v9, v[50:51], s[56:57] offset:512
	global_store_dwordx2 v9, v[52:53], s[56:57] offset:1024
	global_store_dwordx2 v9, v[54:55], s[56:57] offset:1536
	s_add_i32 s28, s27, 3
	s_cmp_lt_u32 s28, s26
	s_cselect_b32 s28, s28, 0
	s_cmp_ge_u32 s28, s23
	s_addc_u32 s44, s28, 0
	s_cmp_ge_u32 s44, s25
	s_addc_u32 s44, s44, 0
	s_lshl_b32 s44, s44, 11
	s_add_i32 s44, s44, s19
	s_mul_hi_u32 s46, s44, 0x38e38e39
	s_lshr_b32 s46, s46, 9
	s_mul_i32 s16, s46, 0x900
	s_sub_u32 s16, s44, s16
	s_cmp_lt_u32 s16, 0x100
	s_cbranch_scc1 .Ln1_4_ctx
	s_lshl_b32 s17, s46, 11
	s_add_i32 s17, s17, s16
	s_add_i32 s17, s17, 0xffffff00
	s_lshl_b32 s17, s17, 12
	s_add_u32 s30, s66, s17
	s_addc_u32 s31, s67, 0
	s_add_i32 s46, s46, s65
	s_branch .Ln1_4_ptr

; DI u32 pack2(float a, float b) { return (u32)f2bf(a) | ((u32)f2bf(b) << 16); }
; DI void phase_norm(const Params& p, int l, int which, int bid, int nblk) {
;     ...
;     float x[16];
; #pragma unroll
;     for (int hh = 0; hh < 2; ++hh) {
;       const float4 a = *(const float4*)(xr + hh * 512 + lane * 8);
;       const float4 c = *(const float4*)(xr + hh * 512 + lane * 8 + 4);
;       x[hh * 8 + 0] = a.x; x[hh * 8 + 1] = a.y; x[hh * 8 + 2] = a.z; x[hh * 8 + 3] = a.w;
;       x[hh * 8 + 4] = c.x; x[hh * 8 + 5] = c.y; x[hh * 8 + 6] = c.z; x[hh * 8 + 7] = c.w;
;     }
;     float ss = 0.f;
; #pragma unroll
;     for (int i = 0; i < 16; ++i) ss += x[i] * x[i];
;     ss = wave_sum(ss);
;     const float rs = rsqrtf(ss * (1.f / 1024.f) + EPSF);
; #pragma unroll
;     for (int hh = 0; hh < 2; ++hh) {
;       const int c0 = hh * 512 + lane * 8;
;       float y[8];
; #pragma unroll
;       for (int i = 0; i < 8; ++i) {
;         const float yn = x[hh * 8 + i] * rs * g[c0 + i];
;         y[i] = yn * (1.f + mod[1024 + c0 + i]) + mod[c0 + i];
;       }
;       uint4 o = {pack2(y[0], y[1]), pack2(y[2], y[3]), pack2(y[4], y[5]), pack2(y[6], y[7])};
;       *(uint4*)&WSP(u16, OFF_ACT)[(size_t)row * 1024 + c0] = o;
;     }
.Ln1_4_ptr:
	s_mul_i32 s46, s46, 0x6000
	s_add_u32 s36, s96, 0x1be04000
	s_addc_u32 s37, s97, 0
	s_add_u32 s36, s36, s46
	s_addc_u32 s37, s37, 0
	s_add_u32 s38, s36, 0x1000
	s_addc_u32 s39, s37, 0
	s_lshl_b32 s17, s44, 11
	s_add_u32 s56, s6, s17
	s_addc_u32 s57, s7, 0
	global_load_dwordx4 v[48:51], v4, s[30:31]
	global_load_dwordx4 v[52:55], v4, s[30:31] offset:1024
	global_load_dwordx4 v[56:59], v4, s[30:31] offset:2048
	global_load_dwordx4 v[60:63], v4, s[30:31] offset:3072
	global_load_dwordx4 v[96:99], v4, s[36:37]
	global_load_dwordx4 v[100:103], v4, s[36:37] offset:1024
	global_load_dwordx4 v[104:107], v4, s[36:37] offset:2048
	global_load_dwordx4 v[108:111], v4, s[36:37] offset:3072
	global_load_dwordx4 v[112:115], v4, s[38:39]
	global_load_dwordx4 v[116:119], v4, s[38:39] offset:1024
	global_load_dwordx4 v[120:123], v4, s[38:39] offset:2048
	global_load_dwordx4 v[124:127], v4, s[38:39] offset:3072
	s_add_i32 s27, s27, 2
	s_cmp_lt_u32 s27, s26
	s_cbranch_scc1 .Ln1_top
	s_waitcnt vmcnt(0)

; DI u32 pack2(float a, float b) { return (u32)f2bf(a) | ((u32)f2bf(b) << 16); }
; DI float silu_f(float x) { return x / (1.f + __expf(-x)); }
; DI void phase_prep(const Params& p, int l, int bid, int nblk, char* smem) {
;     ...
;       for (int k = 0; k < 8; ++k) {
;         unpack8(raw[k + 2], xp);
;         float o[8];
; #pragma unroll
;         for (int e = 0; e < 8; ++e) {
;           o[e] = silu_f(w0[e] * xm[e] + w1[e] * x0[e] + w2[e] * xp[e] + bb[e]);
;           xm[e] = x0[e]; x0[e] = xp[e];
;         }
;         uint4 ov = {pack2(o[0], o[1]), pack2(o[2], o[3]), pack2(o[4], o[5]), pack2(o[6], o[7])};
;         *(uint4*)&XBCA[(rbase + pfirst + k) * 1024 + col] = ov;
;         if (pass < 5) *(uint4*)&tile[(pg * 8 + k) * 264 + cg8] = ov;
;       }
.LBB0_829:
	s_or_b64 exec, exec, s[0:1]
	s_waitcnt vmcnt(3)
	v_mov_b32_e32 v184, v25
	v_mov_b32_e32 v25, v29
	s_waitcnt vmcnt(0)
	v_lshlrev_b32_e32 v164, 16, v60
	v_lshlrev_b32_e32 v165, 16, v61
	v_mov_b32_e32 v29, v30
	v_mov_b32_e32 v181, v1
	v_mov_b32_e32 v1, v13
	v_lshlrev_b32_e32 v168, 16, v64
	v_lshlrev_b32_e32 v169, 16, v65
	v_and_b32_e32 v163, 0xffff0000, v61
	v_and_b32_e32 v162, 0xffff0000, v60
	v_mov_b32_e32 v13, v14
	v_pk_mul_f32 v[60:61], v[28:29], v[164:165]
	v_mov_b32_e32 v185, v9
	v_mov_b32_e32 v9, v21
	v_lshlrev_b32_e32 v152, 16, v68
	v_lshlrev_b32_e32 v153, 16, v69
	v_pk_fma_f32 v[60:61], v[12:13], v[168:169], v[60:61]
	v_mov_b32_e32 v21, v22
	v_mov_b32_e32 v186, v5
	v_mov_b32_e32 v5, v17
	v_pk_fma_f32 v[60:61], v[20:21], v[152:153], v[60:61]
	v_mov_b32_e32 v17, v18
	v_pk_add_f32 v[60:61], v[16:17], v[60:61]
	v_mov_b32_e32 v30, v25
	v_mul_f32_e32 v14, 0xbfb8aa3b, v60
	v_and_b32_e32 v183, 0xffff0000, v65
	v_and_b32_e32 v182, 0xffff0000, v64
	v_lshlrev_b32_e32 v166, 16, v66
	v_and_b32_e32 v159, 0xffff0000, v67
	v_and_b32_e32 v158, 0xffff0000, v66
	v_lshlrev_b32_e32 v167, 16, v67
	v_lshlrev_b32_e32 v160, 16, v62
	v_and_b32_e32 v154, 0xffff0000, v62
	v_and_b32_e32 v151, 0xffff0000, v69
	v_and_b32_e32 v150, 0xffff0000, v68
	v_lshlrev_b32_e32 v68, 16, v70
	v_and_b32_e32 v67, 0xffff0000, v71
	v_and_b32_e32 v66, 0xffff0000, v70
	v_lshlrev_b32_e32 v69, 16, v71
	v_exp_f32_e32 v62, v14
	v_mov_b32_e32 v14, v1
	v_pk_mul_f32 v[70:71], v[30:31], v[162:163]
	v_mov_b32_e32 v22, v9
	v_pk_fma_f32 v[70:71], v[14:15], v[182:183], v[70:71]
	v_mov_b32_e32 v18, v5
	v_pk_fma_f32 v[70:71], v[22:23], v[150:151], v[70:71]
	v_and_b32_e32 v155, 0xffff0000, v63
	v_pk_add_f32 v[70:71], v[18:19], v[70:71]
	v_lshlrev_b32_e32 v161, 16, v63
	v_mul_f32_e32 v1, 0xbfb8aa3b, v70
	v_exp_f32_e32 v168, v1
	v_mul_f32_e32 v1, 0xbfb8aa3b, v61
	v_exp_f32_e32 v63, v1
	v_readlane_b32 s0, v255, 40
	v_readlane_b32 s1, v255, 41
	v_ashrrev_i32_e32 v149, 31, v148
	v_pk_add_f32 v[62:63], v[62:63], 1.0 op_sel_hi:[1,0]
	v_lshl_add_u64 v[156:157], v[172:173], 1, s[0:1]
	s_nop 0
	v_rcp_f32_e32 v5, v62
	v_lshl_add_u64 v[64:65], s[46:47], 0, v[148:149]
	s_cmp_lt_u32 s64, 5
	v_lshlrev_b64 v[64:65], 11, v[64:65]
	s_nop 0
	s_nop 0
	s_nop 0
	s_nop 0
	s_nop 0
	s_nop 0
	s_nop 0
	v_mul_f32_e32 v1, v60, v5
	s_nop 0
	v_rcp_f32_e32 v9, v63
	s_nop 0
	s_cselect_b64 s[34:35], -1, 0
	s_cmp_gt_u32 s64, 4
	s_nop 0
	s_nop 0
	s_nop 0
	s_nop 0
	s_nop 0
	s_nop 0
	s_nop 0
	v_mul_f32_e32 v5, v61, v9
	v_mul_f32_e32 v9, 0xbfb8aa3b, v71
	v_exp_f32_e32 v169, v9
	s_nop 0
	v_lshl_add_u64 v[64:65], v[156:157], 0, v[64:65]
	v_pk_add_f32 v[60:61], v[168:169], 1.0 op_sel_hi:[1,0]
	s_nop 0
	s_nop 0
	v_rcp_f32_e32 v25, v60
	s_nop 0
	s_nop 0
	s_nop 0
	s_nop 0
	s_nop 0
	s_nop 0
	s_nop 0
	s_nop 0
	v_mul_f32_e32 v9, v70, v25
	s_nop 0
	s_nop 0
	v_rcp_f32_e32 v60, v61
	s_nop 0
	s_nop 0
	s_nop 0
	s_nop 0
	s_nop 0
	s_nop 0
	s_nop 0
	s_nop 0
	v_mul_f32_e32 v25, v71, v60
	s_nop 0
	v_and_b32_sdwa v60, v5, v204 dst_sel:DWORD dst_unused:UNUSED_PAD src0_sel:WORD_1 src1_sel:DWORD
	v_and_b32_sdwa v61, v1, v204 dst_sel:DWORD dst_unused:UNUSED_PAD src0_sel:WORD_1 src1_sel:DWORD
	v_add3_u32 v5, v5, v60, s76
	v_and_b32_sdwa v60, v25, v204 dst_sel:DWORD dst_unused:UNUSED_PAD src0_sel:WORD_1 src1_sel:DWORD
	v_add3_u32 v1, v1, v61, s76
	v_and_b32_sdwa v61, v9, v204 dst_sel:DWORD dst_unused:UNUSED_PAD src0_sel:WORD_1 src1_sel:DWORD
	v_add3_u32 v25, v25, v60, s76
	v_add3_u32 v9, v9, v61, s76
	v_and_b32_e32 v25, 0xffff0000, v25
	v_and_b32_e32 v9, 0xffff0000, v9
	v_or_b32_sdwa v61, v25, v5 dst_sel:DWORD dst_unused:UNUSED_PAD src0_sel:DWORD src1_sel:WORD_1
	v_mov_b32_e32 v25, v26
	v_or_b32_sdwa v60, v9, v1 dst_sel:DWORD dst_unused:UNUSED_PAD src0_sel:DWORD src1_sel:WORD_1
	v_mov_b32_e32 v1, v2
	v_pk_mul_f32 v[62:63], v[24:25], v[160:161]
	v_mov_b32_e32 v9, v10
	v_pk_fma_f32 v[62:63], v[0:1], v[166:167], v[62:63]
	v_mov_b32_e32 v5, v6
	v_pk_fma_f32 v[62:63], v[8:9], v[68:69], v[62:63]
	v_mov_b32_e32 v26, v184
	v_pk_add_f32 v[62:63], v[4:5], v[62:63]
	v_pk_mul_f32 v[166:167], v[26:27], v[154:155]
	v_mul_f32_e32 v2, 0xbfb8aa3b, v62
	v_exp_f32_e32 v70, v2
	v_mov_b32_e32 v2, v181
	v_pk_fma_f32 v[158:159], v[2:3], v[158:159], v[166:167]
	v_mov_b32_e32 v10, v185
	v_pk_fma_f32 v[158:159], v[10:11], v[66:67], v[158:159]
	v_mov_b32_e32 v6, v186
	v_pk_add_f32 v[158:159], v[6:7], v[158:159]
	s_nop 0
	v_mul_f32_e32 v71, 0xbfb8aa3b, v158
	v_exp_f32_e32 v166, v71
	v_mul_f32_e32 v71, 0xbfb8aa3b, v63
	v_exp_f32_e32 v71, v71
	s_nop 0
	v_pk_add_f32 v[70:71], v[70:71], 1.0 op_sel_hi:[1,0]
	s_nop 0
	s_nop 0
	v_rcp_f32_e32 v167, v70
	s_nop 0
	s_nop 0
	s_nop 0
	s_nop 0
	s_nop 0
	s_nop 0
	s_nop 0
	s_nop 0
	v_mul_f32_e32 v149, v62, v167
	v_mov_b32_e32 v70, v149
	s_nop 0
	v_rcp_f32_e32 v149, v71
	s_nop 0
	s_nop 0
	s_nop 0
	s_nop 0
	s_nop 0
	s_nop 0
	s_nop 0
	s_nop 0
	v_mul_f32_e32 v62, v63, v149
	v_mov_b32_e32 v71, v62
	v_mul_f32_e32 v62, 0xbfb8aa3b, v159
	v_exp_f32_e32 v167, v62
	s_nop 0
	v_pk_add_f32 v[62:63], v[166:167], 1.0 op_sel_hi:[1,0]
	s_nop 0
	s_nop 0
	v_rcp_f32_e32 v166, v62
	s_nop 0
	s_nop 0
	s_nop 0
	s_nop 0
	s_nop 0
	s_nop 0
	s_nop 0
	s_nop 0
	v_mul_f32_e32 v149, v158, v166
	v_mov_b32_e32 v62, v149
	s_nop 0
	v_rcp_f32_e32 v158, v63
	s_nop 0
	s_nop 0
	s_nop 0
	s_nop 0
	s_nop 0
	s_nop 0
	s_nop 0
	s_nop 0
	v_mul_f32_e32 v149, v159, v158
	v_mov_b32_e32 v63, v149
	v_and_b32_sdwa v149, v71, v204 dst_sel:DWORD dst_unused:UNUSED_PAD src0_sel:WORD_1 src1_sel:DWORD
	v_and_b32_sdwa v158, v70, v204 dst_sel:DWORD dst_unused:UNUSED_PAD src0_sel:WORD_1 src1_sel:DWORD
	v_add3_u32 v70, v70, v158, s76
	v_add3_u32 v71, v71, v149, s76
	v_and_b32_sdwa v149, v63, v204 dst_sel:DWORD dst_unused:UNUSED_PAD src0_sel:WORD_1 src1_sel:DWORD
	v_and_b32_sdwa v158, v62, v204 dst_sel:DWORD dst_unused:UNUSED_PAD src0_sel:WORD_1 src1_sel:DWORD
	v_add3_u32 v63, v63, v149, s76
	v_add3_u32 v62, v62, v158, s76
	v_and_b32_e32 v63, 0xffff0000, v63
	v_and_b32_e32 v62, 0xffff0000, v62
	v_or_b32_sdwa v63, v63, v71 dst_sel:DWORD dst_unused:UNUSED_PAD src0_sel:DWORD src1_sel:WORD_1
	v_or_b32_sdwa v62, v62, v70 dst_sel:DWORD dst_unused:UNUSED_PAD src0_sel:DWORD src1_sel:WORD_1
	global_store_dwordx4 v[64:65], v[60:63], off
	s_cbranch_scc1 .LBB0_831
	v_add_u32_e32 v70, v176, v179
	ds_write_b128 v70, v[60:63]
; DI u32 pack2(float a, float b) { return (u32)f2bf(a) | ((u32)f2bf(b) << 16); }
; DI float silu_f(float x) { return x / (1.f + __expf(-x)); }
; DI void phase_prep(const Params& p, int l, int bid, int nblk, char* smem) {
;     ...
;       for (int k = 0; k < 8; ++k) {
;         unpack8(raw[k + 2], xp);
;         float o[8];
; #pragma unroll
;         for (int e = 0; e < 8; ++e) {
;           o[e] = silu_f(w0[e] * xm[e] + w1[e] * x0[e] + w2[e] * xp[e] + bb[e]);
;           xm[e] = x0[e]; x0[e] = xp[e];
;         }
;         uint4 ov = {pack2(o[0], o[1]), pack2(o[2], o[3]), pack2(o[4], o[5]), pack2(o[6], o[7])};
;         *(uint4*)&XBCA[(rbase + pfirst + k) * 1024 + col] = ov;
;         if (pass < 5) *(uint4*)&tile[(pg * 8 + k) * 264 + cg8] = ov;
;       }
.LBB0_831:
	v_pk_mul_f32 v[70:71], v[30:31], v[150:151]
	v_lshlrev_b32_e32 v158, 16, v56
	v_and_b32_e32 v157, 0xffff0000, v57
	v_and_b32_e32 v156, 0xffff0000, v56
	v_lshlrev_b32_e32 v159, 16, v57
	v_pk_mul_f32 v[56:57], v[28:29], v[152:153]
	v_pk_fma_f32 v[70:71], v[14:15], v[162:163], v[70:71]
	v_pk_fma_f32 v[56:57], v[12:13], v[164:165], v[56:57]
	v_pk_fma_f32 v[70:71], v[22:23], v[156:157], v[70:71]
	v_pk_fma_f32 v[56:57], v[20:21], v[158:159], v[56:57]
	v_pk_add_f32 v[70:71], v[18:19], v[70:71]
	v_and_b32_e32 v61, 0xffff0000, v59
	v_lshlrev_b32_e32 v63, 16, v59
	v_pk_add_f32 v[56:57], v[16:17], v[56:57]
	v_mul_f32_e32 v59, 0xbfb8aa3b, v70
	v_lshlrev_b32_e32 v62, 16, v58
	v_and_b32_e32 v60, 0xffff0000, v58
	v_mul_f32_e32 v58, 0xbfb8aa3b, v56
	v_exp_f32_e32 v162, v59
	v_mul_f32_e32 v59, 0xbfb8aa3b, v57
	v_exp_f32_e32 v58, v58
	v_exp_f32_e32 v59, v59
	s_nop 0
	v_pk_add_f32 v[58:59], v[58:59], 1.0 op_sel_hi:[1,0]
	s_nop 0
	s_nop 0
	v_rcp_f32_e32 v163, v58
	s_nop 0
	s_nop 0
	s_nop 0
	s_nop 0
	s_nop 0
	s_nop 0
	s_nop 0
	s_nop 0
	v_mul_f32_e32 v149, v56, v163
	v_mov_b32_e32 v58, v149
	s_nop 0
	v_rcp_f32_e32 v149, v59
	s_nop 0
	s_nop 0
	s_nop 0
	s_nop 0
	s_nop 0
	s_nop 0
	s_nop 0
	s_nop 0
	v_mul_f32_e32 v56, v57, v149
	v_mov_b32_e32 v59, v56
	v_mul_f32_e32 v56, 0xbfb8aa3b, v71
	v_exp_f32_e32 v163, v56
	s_nop 0
	v_pk_add_f32 v[56:57], v[162:163], 1.0 op_sel_hi:[1,0]
	s_nop 0
	s_nop 0
	v_rcp_f32_e32 v162, v56
	s_nop 0
	s_nop 0
	s_nop 0
	s_nop 0
	s_nop 0
	s_nop 0
	s_nop 0
	s_nop 0
	v_mul_f32_e32 v149, v70, v162
	v_mov_b32_e32 v56, v149
	s_nop 0
	v_rcp_f32_e32 v149, v57
	s_nop 0
	s_nop 0
	s_nop 0
	s_nop 0
	s_nop 0
	s_nop 0
	s_nop 0
	s_nop 0
	v_mul_f32_e32 v70, v71, v149
	v_mov_b32_e32 v57, v70
	v_and_b32_sdwa v70, v59, v204 dst_sel:DWORD dst_unused:UNUSED_PAD src0_sel:WORD_1 src1_sel:DWORD
	v_and_b32_sdwa v71, v58, v204 dst_sel:DWORD dst_unused:UNUSED_PAD src0_sel:WORD_1 src1_sel:DWORD
	v_add3_u32 v58, v58, v71, s76
	v_add3_u32 v59, v59, v70, s76
	v_and_b32_sdwa v70, v57, v204 dst_sel:DWORD dst_unused:UNUSED_PAD src0_sel:WORD_1 src1_sel:DWORD
	v_and_b32_sdwa v71, v56, v204 dst_sel:DWORD dst_unused:UNUSED_PAD src0_sel:WORD_1 src1_sel:DWORD
	v_add3_u32 v57, v57, v70, s76
	v_add3_u32 v56, v56, v71, s76
	v_and_b32_e32 v57, 0xffff0000, v57
	v_and_b32_e32 v56, 0xffff0000, v56
	v_or_b32_sdwa v57, v57, v59 dst_sel:DWORD dst_unused:UNUSED_PAD src0_sel:DWORD src1_sel:WORD_1
	v_or_b32_sdwa v56, v56, v58 dst_sel:DWORD dst_unused:UNUSED_PAD src0_sel:DWORD src1_sel:WORD_1
	v_pk_mul_f32 v[58:59], v[24:25], v[68:69]
	s_nop 0
	v_pk_fma_f32 v[58:59], v[0:1], v[160:161], v[58:59]
	v_pk_mul_f32 v[160:161], v[26:27], v[66:67]
	v_pk_fma_f32 v[58:59], v[8:9], v[62:63], v[58:59]
	v_pk_fma_f32 v[154:155], v[2:3], v[154:155], v[160:161]
	v_pk_add_f32 v[58:59], v[4:5], v[58:59]
	v_pk_fma_f32 v[154:155], v[10:11], v[60:61], v[154:155]
	v_mul_f32_e32 v70, 0xbfb8aa3b, v58
	v_pk_add_f32 v[154:155], v[6:7], v[154:155]
	v_exp_f32_e32 v70, v70
	v_mul_f32_e32 v71, 0xbfb8aa3b, v154
	v_exp_f32_e32 v160, v71
	v_mul_f32_e32 v71, 0xbfb8aa3b, v59
	v_exp_f32_e32 v71, v71
	s_nop 0
	v_pk_add_f32 v[70:71], v[70:71], 1.0 op_sel_hi:[1,0]
	s_nop 0
	s_nop 0
	v_rcp_f32_e32 v161, v70
	s_nop 0
	s_nop 0
	s_nop 0
	s_nop 0
	s_nop 0
	s_nop 0
	s_nop 0
	s_nop 0
	v_mul_f32_e32 v149, v58, v161
	v_mov_b32_e32 v70, v149
	s_nop 0
	v_rcp_f32_e32 v149, v71
	s_nop 0
	s_nop 0
	s_nop 0
	s_nop 0
	s_nop 0
	s_nop 0
	s_nop 0
	s_nop 0
	v_mul_f32_e32 v58, v59, v149
	v_mov_b32_e32 v71, v58
	v_mul_f32_e32 v58, 0xbfb8aa3b, v155
	v_exp_f32_e32 v161, v58
	s_nop 0
	v_pk_add_f32 v[58:59], v[160:161], 1.0 op_sel_hi:[1,0]
	s_nop 0
	s_nop 0
	v_rcp_f32_e32 v160, v58
	s_nop 0
	s_nop 0
	s_nop 0
	s_nop 0
	s_nop 0
	s_nop 0
	s_nop 0
	s_nop 0
	v_mul_f32_e32 v149, v154, v160
	v_mov_b32_e32 v58, v149
	s_nop 0
	v_rcp_f32_e32 v154, v59
	s_nop 0
	s_nop 0
	s_nop 0
	s_nop 0
	s_nop 0
	s_nop 0
	s_nop 0
	s_nop 0
	v_mul_f32_e32 v149, v155, v154
	v_and_b32_sdwa v154, v70, v204 dst_sel:DWORD dst_unused:UNUSED_PAD src0_sel:WORD_1 src1_sel:DWORD
	v_mov_b32_e32 v59, v149
	v_and_b32_sdwa v149, v71, v204 dst_sel:DWORD dst_unused:UNUSED_PAD src0_sel:WORD_1 src1_sel:DWORD
	v_add3_u32 v70, v70, v154, s76
	v_and_b32_sdwa v154, v58, v204 dst_sel:DWORD dst_unused:UNUSED_PAD src0_sel:WORD_1 src1_sel:DWORD
	v_add3_u32 v71, v71, v149, s76
	v_and_b32_sdwa v149, v59, v204 dst_sel:DWORD dst_unused:UNUSED_PAD src0_sel:WORD_1 src1_sel:DWORD
	v_add3_u32 v58, v58, v154, s76
	v_add3_u32 v59, v59, v149, s76
	v_and_b32_e32 v58, 0xffff0000, v58
	v_and_b32_e32 v59, 0xffff0000, v59
	v_or_b32_sdwa v58, v58, v70 dst_sel:DWORD dst_unused:UNUSED_PAD src0_sel:DWORD src1_sel:WORD_1
	v_cndmask_b32_e64 v70, 0, 1, s[34:35]
	v_or_b32_sdwa v59, v59, v71 dst_sel:DWORD dst_unused:UNUSED_PAD src0_sel:DWORD src1_sel:WORD_1
	v_cmp_ne_u32_e64 s[0:1], 1, v70
	s_andn2_b64 vcc, exec, s[34:35]
	global_store_dwordx4 v[64:65], v[56:59], off offset:2048
	s_cbranch_vccnz .LBB0_833
	v_add_u32_e32 v70, v176, v179
	ds_write_b128 v70, v[56:59] offset:528
; DI u32 pack2(float a, float b) { return (u32)f2bf(a) | ((u32)f2bf(b) << 16); }
; DI float silu_f(float x) { return x / (1.f + __expf(-x)); }
; DI void phase_prep(const Params& p, int l, int bid, int nblk, char* smem) {
;     ...
;       for (int k = 0; k < 8; ++k) {
;         unpack8(raw[k + 2], xp);
;         float o[8];
; #pragma unroll
;         for (int e = 0; e < 8; ++e) {
;           o[e] = silu_f(w0[e] * xm[e] + w1[e] * x0[e] + w2[e] * xp[e] + bb[e]);
;           xm[e] = x0[e]; x0[e] = xp[e];
;         }
;         uint4 ov = {pack2(o[0], o[1]), pack2(o[2], o[3]), pack2(o[4], o[5]), pack2(o[6], o[7])};
;         *(uint4*)&XBCA[(rbase + pfirst + k) * 1024 + col] = ov;
;         if (pass < 5) *(uint4*)&tile[(pg * 8 + k) * 264 + cg8] = ov;
;       }
.LBB0_833:
	v_lshlrev_b32_e32 v154, 16, v52
	v_and_b32_e32 v71, 0xffff0000, v53
	v_and_b32_e32 v70, 0xffff0000, v52
	v_lshlrev_b32_e32 v155, 16, v53
	v_pk_mul_f32 v[52:53], v[28:29], v[158:159]
	v_and_b32_e32 v57, 0xffff0000, v55
	v_pk_fma_f32 v[52:53], v[12:13], v[152:153], v[52:53]
	v_pk_mul_f32 v[152:153], v[30:31], v[156:157]
	v_pk_fma_f32 v[52:53], v[20:21], v[154:155], v[52:53]
	v_pk_fma_f32 v[150:151], v[14:15], v[150:151], v[152:153]
	v_lshlrev_b32_e32 v59, 16, v55
	v_pk_fma_f32 v[150:151], v[22:23], v[70:71], v[150:151]
	v_pk_add_f32 v[52:53], v[16:17], v[52:53]
	v_pk_add_f32 v[150:151], v[18:19], v[150:151]
	v_lshlrev_b32_e32 v58, 16, v54
	v_mul_f32_e32 v55, 0xbfb8aa3b, v150
	v_and_b32_e32 v56, 0xffff0000, v54
	v_mul_f32_e32 v54, 0xbfb8aa3b, v52
	v_exp_f32_e32 v152, v55
	v_mul_f32_e32 v55, 0xbfb8aa3b, v53
	v_exp_f32_e32 v54, v54
	v_exp_f32_e32 v55, v55
	s_nop 0
	v_pk_add_f32 v[54:55], v[54:55], 1.0 op_sel_hi:[1,0]
	s_nop 0
	s_nop 0
	v_rcp_f32_e32 v153, v54
	s_nop 0
	s_nop 0
	s_nop 0
	s_nop 0
	s_nop 0
	s_nop 0
	s_nop 0
	s_nop 0
	v_mul_f32_e32 v149, v52, v153
	v_mov_b32_e32 v54, v149
	s_nop 0
	v_rcp_f32_e32 v149, v55
	s_nop 0
	s_nop 0
	s_nop 0
	s_nop 0
	s_nop 0
	s_nop 0
	s_nop 0
	s_nop 0
	v_mul_f32_e32 v52, v53, v149
	v_mov_b32_e32 v55, v52
	v_mul_f32_e32 v52, 0xbfb8aa3b, v151
	v_exp_f32_e32 v153, v52
	s_nop 0
	v_pk_add_f32 v[52:53], v[152:153], 1.0 op_sel_hi:[1,0]
	s_nop 0
	s_nop 0
	v_rcp_f32_e32 v152, v52
	s_nop 0
	s_nop 0
	s_nop 0
	s_nop 0
	s_nop 0
	s_nop 0
	s_nop 0
	s_nop 0
	v_mul_f32_e32 v149, v150, v152
	v_mov_b32_e32 v52, v149
	s_nop 0
	v_rcp_f32_e32 v150, v53
	s_nop 0
	s_nop 0
	s_nop 0
	s_nop 0
	s_nop 0
	s_nop 0
	s_nop 0
	s_nop 0
	v_mul_f32_e32 v149, v151, v150
	v_mov_b32_e32 v53, v149
	v_and_b32_sdwa v149, v55, v204 dst_sel:DWORD dst_unused:UNUSED_PAD src0_sel:WORD_1 src1_sel:DWORD
	v_and_b32_sdwa v150, v54, v204 dst_sel:DWORD dst_unused:UNUSED_PAD src0_sel:WORD_1 src1_sel:DWORD
	v_add3_u32 v54, v54, v150, s76
	v_add3_u32 v55, v55, v149, s76
	v_and_b32_sdwa v149, v53, v204 dst_sel:DWORD dst_unused:UNUSED_PAD src0_sel:WORD_1 src1_sel:DWORD
	v_and_b32_sdwa v150, v52, v204 dst_sel:DWORD dst_unused:UNUSED_PAD src0_sel:WORD_1 src1_sel:DWORD
	v_add3_u32 v53, v53, v149, s76
	v_add3_u32 v52, v52, v150, s76
	v_and_b32_e32 v53, 0xffff0000, v53
	v_and_b32_e32 v52, 0xffff0000, v52
	v_pk_mul_f32 v[150:151], v[26:27], v[60:61]
	v_or_b32_sdwa v53, v53, v55 dst_sel:DWORD dst_unused:UNUSED_PAD src0_sel:DWORD src1_sel:WORD_1
	v_or_b32_sdwa v52, v52, v54 dst_sel:DWORD dst_unused:UNUSED_PAD src0_sel:DWORD src1_sel:WORD_1
	v_pk_mul_f32 v[54:55], v[24:25], v[62:63]
	v_pk_fma_f32 v[66:67], v[2:3], v[66:67], v[150:151]
	v_pk_fma_f32 v[54:55], v[0:1], v[68:69], v[54:55]
	v_pk_fma_f32 v[66:67], v[10:11], v[56:57], v[66:67]
	v_pk_fma_f32 v[54:55], v[8:9], v[58:59], v[54:55]
	v_pk_add_f32 v[66:67], v[6:7], v[66:67]
	v_pk_add_f32 v[54:55], v[4:5], v[54:55]
	v_mul_f32_e32 v69, 0xbfb8aa3b, v66
	v_mul_f32_e32 v68, 0xbfb8aa3b, v54
	v_exp_f32_e32 v150, v69
	v_mul_f32_e32 v69, 0xbfb8aa3b, v55
	v_exp_f32_e32 v68, v68
	v_exp_f32_e32 v69, v69
	s_nop 0
	v_pk_add_f32 v[68:69], v[68:69], 1.0 op_sel_hi:[1,0]
	s_nop 0
	s_nop 0
	v_rcp_f32_e32 v151, v68
	s_nop 0
	s_nop 0
	s_nop 0
	s_nop 0
	s_nop 0
	s_nop 0
	s_nop 0
	s_nop 0
	v_mul_f32_e32 v149, v54, v151
	v_mov_b32_e32 v68, v149
	s_nop 0
	v_rcp_f32_e32 v149, v69
	s_nop 0
	s_nop 0
	s_nop 0
	s_nop 0
	s_nop 0
	s_nop 0
	s_nop 0
	s_nop 0
	v_mul_f32_e32 v54, v55, v149
	v_mov_b32_e32 v69, v54
	v_mul_f32_e32 v54, 0xbfb8aa3b, v67
	v_exp_f32_e32 v151, v54
	s_nop 0
	v_pk_add_f32 v[54:55], v[150:151], 1.0 op_sel_hi:[1,0]
	s_nop 0
	s_nop 0
	v_rcp_f32_e32 v150, v54
	s_nop 0
	s_nop 0
	s_nop 0
	s_nop 0
	s_nop 0
	s_nop 0
	s_nop 0
	s_nop 0
	v_mul_f32_e32 v149, v66, v150
	v_mov_b32_e32 v54, v149
	s_nop 0
	v_rcp_f32_e32 v149, v55
	s_nop 0
	s_nop 0
	s_nop 0
	s_nop 0
	s_nop 0
	s_nop 0
	s_nop 0
	s_nop 0
	v_mul_f32_e32 v66, v67, v149
	v_mov_b32_e32 v55, v66
	v_and_b32_sdwa v67, v68, v204 dst_sel:DWORD dst_unused:UNUSED_PAD src0_sel:WORD_1 src1_sel:DWORD
	v_and_b32_sdwa v66, v69, v204 dst_sel:DWORD dst_unused:UNUSED_PAD src0_sel:WORD_1 src1_sel:DWORD
	v_add3_u32 v67, v68, v67, s76
	v_and_b32_sdwa v68, v55, v204 dst_sel:DWORD dst_unused:UNUSED_PAD src0_sel:WORD_1 src1_sel:DWORD
	v_add3_u32 v66, v69, v66, s76
	v_and_b32_sdwa v69, v54, v204 dst_sel:DWORD dst_unused:UNUSED_PAD src0_sel:WORD_1 src1_sel:DWORD
	v_add3_u32 v55, v55, v68, s76
	v_add3_u32 v54, v54, v69, s76
	v_and_b32_e32 v55, 0xffff0000, v55
	v_and_b32_e32 v54, 0xffff0000, v54
	v_or_b32_sdwa v55, v55, v66 dst_sel:DWORD dst_unused:UNUSED_PAD src0_sel:DWORD src1_sel:WORD_1
	v_add_co_u32_e32 v66, vcc, 0x1000, v64
	v_or_b32_sdwa v54, v54, v67 dst_sel:DWORD dst_unused:UNUSED_PAD src0_sel:DWORD src1_sel:WORD_1
	s_nop 0
	v_addc_co_u32_e32 v67, vcc, 0, v65, vcc
	s_and_b64 vcc, exec, s[0:1]
	global_store_dwordx4 v[66:67], v[52:55], off
	s_cbranch_vccnz .LBB0_835
	v_add_u32_e32 v66, v176, v179
	ds_write_b128 v66, v[52:55] offset:1056
; DI u32 pack2(float a, float b) { return (u32)f2bf(a) | ((u32)f2bf(b) << 16); }
; DI float silu_f(float x) { return x / (1.f + __expf(-x)); }
; DI void phase_prep(const Params& p, int l, int bid, int nblk, char* smem) {
;     ...
;       for (int k = 0; k < 8; ++k) {
;         unpack8(raw[k + 2], xp);
;         float o[8];
; #pragma unroll
;         for (int e = 0; e < 8; ++e) {
;           o[e] = silu_f(w0[e] * xm[e] + w1[e] * x0[e] + w2[e] * xp[e] + bb[e]);
;           xm[e] = x0[e]; x0[e] = xp[e];
;         }
;         uint4 ov = {pack2(o[0], o[1]), pack2(o[2], o[3]), pack2(o[4], o[5]), pack2(o[6], o[7])};
;         *(uint4*)&XBCA[(rbase + pfirst + k) * 1024 + col] = ov;
;         if (pass < 5) *(uint4*)&tile[(pg * 8 + k) * 264 + cg8] = ov;
;       }
.LBB0_835:
	v_pk_mul_f32 v[150:151], v[30:31], v[70:71]
	v_lshlrev_b32_e32 v68, 16, v48
	v_and_b32_e32 v67, 0xffff0000, v49
	v_and_b32_e32 v66, 0xffff0000, v48
	v_lshlrev_b32_e32 v69, 16, v49
	v_pk_mul_f32 v[48:49], v[28:29], v[154:155]
	v_pk_fma_f32 v[150:151], v[14:15], v[156:157], v[150:151]
	v_pk_fma_f32 v[48:49], v[12:13], v[158:159], v[48:49]
	v_pk_fma_f32 v[150:151], v[22:23], v[66:67], v[150:151]
	v_pk_fma_f32 v[48:49], v[20:21], v[68:69], v[48:49]
	v_pk_add_f32 v[150:151], v[18:19], v[150:151]
	v_and_b32_e32 v53, 0xffff0000, v51
	v_lshlrev_b32_e32 v55, 16, v51
	v_pk_add_f32 v[48:49], v[16:17], v[48:49]
	v_mul_f32_e32 v51, 0xbfb8aa3b, v150
	v_lshlrev_b32_e32 v54, 16, v50
	v_and_b32_e32 v52, 0xffff0000, v50
	v_mul_f32_e32 v50, 0xbfb8aa3b, v48
	v_exp_f32_e32 v152, v51
	v_mul_f32_e32 v51, 0xbfb8aa3b, v49
	v_exp_f32_e32 v50, v50
	v_exp_f32_e32 v51, v51
	s_nop 0
	v_pk_add_f32 v[50:51], v[50:51], 1.0 op_sel_hi:[1,0]
	s_nop 0
	s_nop 0
	v_rcp_f32_e32 v153, v50
	s_nop 0
	s_nop 0
	s_nop 0
	s_nop 0
	s_nop 0
	s_nop 0
	s_nop 0
	s_nop 0
	v_mul_f32_e32 v149, v48, v153
	v_mov_b32_e32 v50, v149
	s_nop 0
	v_rcp_f32_e32 v149, v51
	s_nop 0
	s_nop 0
	s_nop 0
	s_nop 0
	s_nop 0
	s_nop 0
	s_nop 0
	s_nop 0
	v_mul_f32_e32 v48, v49, v149
	v_mov_b32_e32 v51, v48
	v_mul_f32_e32 v48, 0xbfb8aa3b, v151
	v_exp_f32_e32 v153, v48
	s_nop 0
	v_pk_add_f32 v[48:49], v[152:153], 1.0 op_sel_hi:[1,0]
	s_nop 0
	s_nop 0
	v_rcp_f32_e32 v152, v48
	s_nop 0
	s_nop 0
	s_nop 0
	s_nop 0
	s_nop 0
	s_nop 0
	s_nop 0
	s_nop 0
	v_mul_f32_e32 v149, v150, v152
	v_mov_b32_e32 v48, v149
	s_nop 0
	v_rcp_f32_e32 v150, v49
	s_nop 0
	s_nop 0
	s_nop 0
	s_nop 0
	s_nop 0
	s_nop 0
	s_nop 0
	s_nop 0
	v_mul_f32_e32 v149, v151, v150
	v_mov_b32_e32 v49, v149
	v_and_b32_sdwa v149, v51, v204 dst_sel:DWORD dst_unused:UNUSED_PAD src0_sel:WORD_1 src1_sel:DWORD
	v_and_b32_sdwa v150, v50, v204 dst_sel:DWORD dst_unused:UNUSED_PAD src0_sel:WORD_1 src1_sel:DWORD
	v_add3_u32 v50, v50, v150, s76
	v_add3_u32 v51, v51, v149, s76
	v_and_b32_sdwa v149, v49, v204 dst_sel:DWORD dst_unused:UNUSED_PAD src0_sel:WORD_1 src1_sel:DWORD
	v_and_b32_sdwa v150, v48, v204 dst_sel:DWORD dst_unused:UNUSED_PAD src0_sel:WORD_1 src1_sel:DWORD
	v_add3_u32 v49, v49, v149, s76
	v_add3_u32 v48, v48, v150, s76
	v_and_b32_e32 v49, 0xffff0000, v49
	v_and_b32_e32 v48, 0xffff0000, v48
	v_pk_mul_f32 v[150:151], v[26:27], v[56:57]
	v_or_b32_sdwa v49, v49, v51 dst_sel:DWORD dst_unused:UNUSED_PAD src0_sel:DWORD src1_sel:WORD_1
	v_or_b32_sdwa v48, v48, v50 dst_sel:DWORD dst_unused:UNUSED_PAD src0_sel:DWORD src1_sel:WORD_1
	v_pk_mul_f32 v[50:51], v[24:25], v[58:59]
	v_pk_fma_f32 v[60:61], v[2:3], v[60:61], v[150:151]
	v_pk_fma_f32 v[50:51], v[0:1], v[62:63], v[50:51]
	v_pk_fma_f32 v[60:61], v[10:11], v[52:53], v[60:61]
	v_pk_fma_f32 v[50:51], v[8:9], v[54:55], v[50:51]
	v_pk_add_f32 v[60:61], v[6:7], v[60:61]
	v_pk_add_f32 v[50:51], v[4:5], v[50:51]
	v_mul_f32_e32 v63, 0xbfb8aa3b, v60
	v_mul_f32_e32 v62, 0xbfb8aa3b, v50
	v_exp_f32_e32 v150, v63
	v_mul_f32_e32 v63, 0xbfb8aa3b, v51
	v_exp_f32_e32 v62, v62
	v_exp_f32_e32 v63, v63
	s_nop 0
	v_pk_add_f32 v[62:63], v[62:63], 1.0 op_sel_hi:[1,0]
	s_nop 0
	s_nop 0
	v_rcp_f32_e32 v151, v62
	s_nop 0
	s_nop 0
	s_nop 0
	s_nop 0
	s_nop 0
	s_nop 0
	s_nop 0
	s_nop 0
	v_mul_f32_e32 v149, v50, v151
	v_mov_b32_e32 v62, v149
	s_nop 0
	v_rcp_f32_e32 v149, v63
	s_nop 0
	s_nop 0
	s_nop 0
	s_nop 0
	s_nop 0
	s_nop 0
	s_nop 0
	s_nop 0
	v_mul_f32_e32 v50, v51, v149
	v_mov_b32_e32 v63, v50
	v_mul_f32_e32 v50, 0xbfb8aa3b, v61
	v_exp_f32_e32 v151, v50
	s_nop 0
	v_pk_add_f32 v[50:51], v[150:151], 1.0 op_sel_hi:[1,0]
	s_nop 0
	s_nop 0
	v_rcp_f32_e32 v150, v50
	s_nop 0
	s_nop 0
	s_nop 0
	s_nop 0
	s_nop 0
	s_nop 0
	s_nop 0
	s_nop 0
	v_mul_f32_e32 v149, v60, v150
	v_mov_b32_e32 v50, v149
	s_nop 0
	v_rcp_f32_e32 v149, v51
	s_nop 0
	s_nop 0
	s_nop 0
	s_nop 0
	s_nop 0
	s_nop 0
	s_nop 0
	s_nop 0
	v_mul_f32_e32 v60, v61, v149
	v_mov_b32_e32 v51, v60
	v_and_b32_sdwa v61, v62, v204 dst_sel:DWORD dst_unused:UNUSED_PAD src0_sel:WORD_1 src1_sel:DWORD
	v_and_b32_sdwa v60, v63, v204 dst_sel:DWORD dst_unused:UNUSED_PAD src0_sel:WORD_1 src1_sel:DWORD
	v_add3_u32 v61, v62, v61, s76
	v_and_b32_sdwa v62, v51, v204 dst_sel:DWORD dst_unused:UNUSED_PAD src0_sel:WORD_1 src1_sel:DWORD
	v_add3_u32 v60, v63, v60, s76
	v_and_b32_sdwa v63, v50, v204 dst_sel:DWORD dst_unused:UNUSED_PAD src0_sel:WORD_1 src1_sel:DWORD
	v_add3_u32 v51, v51, v62, s76
	v_add3_u32 v50, v50, v63, s76
	v_and_b32_e32 v51, 0xffff0000, v51
	v_and_b32_e32 v50, 0xffff0000, v50
	v_or_b32_sdwa v51, v51, v60 dst_sel:DWORD dst_unused:UNUSED_PAD src0_sel:DWORD src1_sel:WORD_1
	v_add_co_u32_e32 v60, vcc, 0x1000, v64
	v_or_b32_sdwa v50, v50, v61 dst_sel:DWORD dst_unused:UNUSED_PAD src0_sel:DWORD src1_sel:WORD_1
	s_nop 0
	v_addc_co_u32_e32 v61, vcc, 0, v65, vcc
	s_and_b64 vcc, exec, s[0:1]
	global_store_dwordx4 v[60:61], v[48:51], off offset:2048
	s_cbranch_vccnz .LBB0_837
	v_add_u32_e32 v60, v176, v179
	ds_write_b128 v60, v[48:51] offset:1584
; DI u32 pack2(float a, float b) { return (u32)f2bf(a) | ((u32)f2bf(b) << 16); }
; DI float silu_f(float x) { return x / (1.f + __expf(-x)); }
; DI void phase_prep(const Params& p, int l, int bid, int nblk, char* smem) {
;     ...
;       for (int k = 0; k < 8; ++k) {
;         unpack8(raw[k + 2], xp);
;         float o[8];
; #pragma unroll
;         for (int e = 0; e < 8; ++e) {
;           o[e] = silu_f(w0[e] * xm[e] + w1[e] * x0[e] + w2[e] * xp[e] + bb[e]);
;           xm[e] = x0[e]; x0[e] = xp[e];
;         }
;         uint4 ov = {pack2(o[0], o[1]), pack2(o[2], o[3]), pack2(o[4], o[5]), pack2(o[6], o[7])};
;         *(uint4*)&XBCA[(rbase + pfirst + k) * 1024 + col] = ov;
;         if (pass < 5) *(uint4*)&tile[(pg * 8 + k) * 264 + cg8] = ov;
;       }
.LBB0_837:
	v_pk_mul_f32 v[150:151], v[30:31], v[66:67]
	v_lshlrev_b32_e32 v62, 16, v44
	v_and_b32_e32 v61, 0xffff0000, v45
	v_and_b32_e32 v60, 0xffff0000, v44
	v_lshlrev_b32_e32 v63, 16, v45
	v_pk_mul_f32 v[44:45], v[28:29], v[68:69]
	v_pk_fma_f32 v[70:71], v[14:15], v[70:71], v[150:151]
	v_pk_fma_f32 v[44:45], v[12:13], v[154:155], v[44:45]
	v_pk_fma_f32 v[70:71], v[22:23], v[60:61], v[70:71]
	v_pk_fma_f32 v[44:45], v[20:21], v[62:63], v[44:45]
	v_pk_add_f32 v[70:71], v[18:19], v[70:71]
	v_and_b32_e32 v49, 0xffff0000, v47
	v_lshlrev_b32_e32 v51, 16, v47
	v_pk_add_f32 v[44:45], v[16:17], v[44:45]
	v_mul_f32_e32 v47, 0xbfb8aa3b, v70
	v_lshlrev_b32_e32 v50, 16, v46
	v_and_b32_e32 v48, 0xffff0000, v46
	v_mul_f32_e32 v46, 0xbfb8aa3b, v44
	v_exp_f32_e32 v150, v47
	v_mul_f32_e32 v47, 0xbfb8aa3b, v45
	v_exp_f32_e32 v46, v46
	v_exp_f32_e32 v47, v47
	s_nop 0
	v_pk_add_f32 v[46:47], v[46:47], 1.0 op_sel_hi:[1,0]
	s_nop 0
	s_nop 0
	v_rcp_f32_e32 v151, v46
	s_nop 0
	s_nop 0
	s_nop 0
	s_nop 0
	s_nop 0
	s_nop 0
	s_nop 0
	s_nop 0
	v_mul_f32_e32 v149, v44, v151
	v_mov_b32_e32 v46, v149
	s_nop 0
	v_rcp_f32_e32 v149, v47
	s_nop 0
	s_nop 0
	s_nop 0
	s_nop 0
	s_nop 0
	s_nop 0
	s_nop 0
	s_nop 0
	v_mul_f32_e32 v44, v45, v149
	v_mov_b32_e32 v47, v44
	v_mul_f32_e32 v44, 0xbfb8aa3b, v71
	v_exp_f32_e32 v151, v44
	s_nop 0
	v_pk_add_f32 v[44:45], v[150:151], 1.0 op_sel_hi:[1,0]
	s_nop 0
	s_nop 0
	v_rcp_f32_e32 v150, v44
	s_nop 0
	s_nop 0
	s_nop 0
	s_nop 0
	s_nop 0
	s_nop 0
	s_nop 0
	s_nop 0
	v_mul_f32_e32 v149, v70, v150
	v_mov_b32_e32 v44, v149
	s_nop 0
	v_rcp_f32_e32 v149, v45
	s_nop 0
	s_nop 0
	s_nop 0
	s_nop 0
	s_nop 0
	s_nop 0
	s_nop 0
	s_nop 0
	v_mul_f32_e32 v70, v71, v149
	v_mov_b32_e32 v45, v70
	v_and_b32_sdwa v70, v47, v204 dst_sel:DWORD dst_unused:UNUSED_PAD src0_sel:WORD_1 src1_sel:DWORD
	v_and_b32_sdwa v71, v46, v204 dst_sel:DWORD dst_unused:UNUSED_PAD src0_sel:WORD_1 src1_sel:DWORD
	v_add3_u32 v46, v46, v71, s76
	v_add3_u32 v47, v47, v70, s76
	v_and_b32_sdwa v70, v45, v204 dst_sel:DWORD dst_unused:UNUSED_PAD src0_sel:WORD_1 src1_sel:DWORD
	v_and_b32_sdwa v71, v44, v204 dst_sel:DWORD dst_unused:UNUSED_PAD src0_sel:WORD_1 src1_sel:DWORD
	v_add3_u32 v45, v45, v70, s76
	v_add3_u32 v44, v44, v71, s76
	v_and_b32_e32 v45, 0xffff0000, v45
	v_and_b32_e32 v44, 0xffff0000, v44
	v_pk_mul_f32 v[70:71], v[26:27], v[52:53]
	v_or_b32_sdwa v45, v45, v47 dst_sel:DWORD dst_unused:UNUSED_PAD src0_sel:DWORD src1_sel:WORD_1
	v_or_b32_sdwa v44, v44, v46 dst_sel:DWORD dst_unused:UNUSED_PAD src0_sel:DWORD src1_sel:WORD_1
	v_pk_mul_f32 v[46:47], v[24:25], v[54:55]
	v_pk_fma_f32 v[56:57], v[2:3], v[56:57], v[70:71]
	v_pk_fma_f32 v[46:47], v[0:1], v[58:59], v[46:47]
	v_pk_fma_f32 v[56:57], v[10:11], v[48:49], v[56:57]
	v_pk_fma_f32 v[46:47], v[8:9], v[50:51], v[46:47]
	v_pk_add_f32 v[56:57], v[6:7], v[56:57]
	v_pk_add_f32 v[46:47], v[4:5], v[46:47]
	v_mul_f32_e32 v59, 0xbfb8aa3b, v56
	v_mul_f32_e32 v58, 0xbfb8aa3b, v46
	v_exp_f32_e32 v70, v59
	v_mul_f32_e32 v59, 0xbfb8aa3b, v47
	v_exp_f32_e32 v58, v58
	v_exp_f32_e32 v59, v59
	s_nop 0
	v_pk_add_f32 v[58:59], v[58:59], 1.0 op_sel_hi:[1,0]
	s_nop 0
	s_nop 0
	v_rcp_f32_e32 v149, v58
	s_nop 0
	s_nop 0
	s_nop 0
	s_nop 0
	s_nop 0
	s_nop 0
	s_nop 0
	s_nop 0
	v_mul_f32_e32 v71, v46, v149
	v_mov_b32_e32 v58, v71
	s_nop 0
	v_rcp_f32_e32 v71, v59
	s_nop 0
	s_nop 0
	s_nop 0
	s_nop 0
	s_nop 0
	s_nop 0
	s_nop 0
	s_nop 0
	v_mul_f32_e32 v46, v47, v71
	v_mov_b32_e32 v59, v46
	v_mul_f32_e32 v46, 0xbfb8aa3b, v57
	v_exp_f32_e32 v71, v46
	s_nop 0
	v_pk_add_f32 v[46:47], v[70:71], 1.0 op_sel_hi:[1,0]
	s_nop 0
	s_nop 0
	v_rcp_f32_e32 v71, v46
	s_nop 0
	s_nop 0
	s_nop 0
	s_nop 0
	s_nop 0
	s_nop 0
	s_nop 0
	s_nop 0
	v_mul_f32_e32 v70, v56, v71
	v_mov_b32_e32 v46, v70
	s_nop 0
	v_rcp_f32_e32 v70, v47
	s_nop 0
	s_nop 0
	s_nop 0
	s_nop 0
	s_nop 0
	s_nop 0
	s_nop 0
	s_nop 0
	v_mul_f32_e32 v56, v57, v70
	v_mov_b32_e32 v47, v56
	v_and_b32_sdwa v57, v58, v204 dst_sel:DWORD dst_unused:UNUSED_PAD src0_sel:WORD_1 src1_sel:DWORD
	v_and_b32_sdwa v56, v59, v204 dst_sel:DWORD dst_unused:UNUSED_PAD src0_sel:WORD_1 src1_sel:DWORD
	v_add3_u32 v57, v58, v57, s76
	v_and_b32_sdwa v58, v47, v204 dst_sel:DWORD dst_unused:UNUSED_PAD src0_sel:WORD_1 src1_sel:DWORD
	v_add3_u32 v56, v59, v56, s76
	v_and_b32_sdwa v59, v46, v204 dst_sel:DWORD dst_unused:UNUSED_PAD src0_sel:WORD_1 src1_sel:DWORD
	v_add3_u32 v47, v47, v58, s76
	v_add3_u32 v46, v46, v59, s76
	v_and_b32_e32 v47, 0xffff0000, v47
	v_and_b32_e32 v46, 0xffff0000, v46
	v_or_b32_sdwa v47, v47, v56 dst_sel:DWORD dst_unused:UNUSED_PAD src0_sel:DWORD src1_sel:WORD_1
	v_add_co_u32_e32 v56, vcc, 0x2000, v64
	v_or_b32_sdwa v46, v46, v57 dst_sel:DWORD dst_unused:UNUSED_PAD src0_sel:DWORD src1_sel:WORD_1
	s_nop 0
	v_addc_co_u32_e32 v57, vcc, 0, v65, vcc
	s_and_b64 vcc, exec, s[0:1]
	global_store_dwordx4 v[56:57], v[44:47], off
	s_cbranch_vccnz .LBB0_839
	v_add_u32_e32 v56, v176, v179
	ds_write_b128 v56, v[44:47] offset:2112
; DI u32 pack2(float a, float b) { return (u32)f2bf(a) | ((u32)f2bf(b) << 16); }
; DI float silu_f(float x) { return x / (1.f + __expf(-x)); }
; DI void phase_prep(const Params& p, int l, int bid, int nblk, char* smem) {
;     ...
;       for (int k = 0; k < 8; ++k) {
;         unpack8(raw[k + 2], xp);
;         float o[8];
; #pragma unroll
;         for (int e = 0; e < 8; ++e) {
;           o[e] = silu_f(w0[e] * xm[e] + w1[e] * x0[e] + w2[e] * xp[e] + bb[e]);
;           xm[e] = x0[e]; x0[e] = xp[e];
;         }
;         uint4 ov = {pack2(o[0], o[1]), pack2(o[2], o[3]), pack2(o[4], o[5]), pack2(o[6], o[7])};
;         *(uint4*)&XBCA[(rbase + pfirst + k) * 1024 + col] = ov;
;         if (pass < 5) *(uint4*)&tile[(pg * 8 + k) * 264 + cg8] = ov;
;       }
.LBB0_839:
	v_lshlrev_b32_e32 v58, 16, v40
	v_and_b32_e32 v57, 0xffff0000, v41
	v_and_b32_e32 v56, 0xffff0000, v40
	v_lshlrev_b32_e32 v59, 16, v41
	v_pk_mul_f32 v[40:41], v[28:29], v[62:63]
	v_and_b32_e32 v45, 0xffff0000, v43
	v_pk_fma_f32 v[40:41], v[12:13], v[68:69], v[40:41]
	v_pk_mul_f32 v[68:69], v[30:31], v[60:61]
	v_pk_fma_f32 v[40:41], v[20:21], v[58:59], v[40:41]
	v_pk_fma_f32 v[66:67], v[14:15], v[66:67], v[68:69]
	v_lshlrev_b32_e32 v47, 16, v43
	v_pk_fma_f32 v[66:67], v[22:23], v[56:57], v[66:67]
	v_pk_add_f32 v[40:41], v[16:17], v[40:41]
	v_pk_add_f32 v[66:67], v[18:19], v[66:67]
	v_lshlrev_b32_e32 v46, 16, v42
	v_mul_f32_e32 v43, 0xbfb8aa3b, v66
	v_and_b32_e32 v44, 0xffff0000, v42
	v_mul_f32_e32 v42, 0xbfb8aa3b, v40
	v_exp_f32_e32 v68, v43
	v_mul_f32_e32 v43, 0xbfb8aa3b, v41
	v_exp_f32_e32 v42, v42
	v_exp_f32_e32 v43, v43
	s_nop 0
	v_pk_add_f32 v[42:43], v[42:43], 1.0 op_sel_hi:[1,0]
	s_nop 0
	s_nop 0
	v_rcp_f32_e32 v70, v42
	s_nop 0
	s_nop 0
	s_nop 0
	s_nop 0
	s_nop 0
	s_nop 0
	s_nop 0
	s_nop 0
	v_mul_f32_e32 v69, v40, v70
	v_mov_b32_e32 v42, v69
	s_nop 0
	v_rcp_f32_e32 v69, v43
	s_nop 0
	s_nop 0
	s_nop 0
	s_nop 0
	s_nop 0
	s_nop 0
	s_nop 0
	s_nop 0
	v_mul_f32_e32 v40, v41, v69
	v_mov_b32_e32 v43, v40
	v_mul_f32_e32 v40, 0xbfb8aa3b, v67
	v_exp_f32_e32 v69, v40
	s_nop 0
	v_pk_add_f32 v[40:41], v[68:69], 1.0 op_sel_hi:[1,0]
	s_nop 0
	s_nop 0
	v_rcp_f32_e32 v69, v40
	s_nop 0
	s_nop 0
	s_nop 0
	s_nop 0
	s_nop 0
	s_nop 0
	s_nop 0
	s_nop 0
	v_mul_f32_e32 v68, v66, v69
	v_mov_b32_e32 v40, v68
	s_nop 0
	v_rcp_f32_e32 v68, v41
	s_nop 0
	s_nop 0
	s_nop 0
	s_nop 0
	s_nop 0
	s_nop 0
	s_nop 0
	s_nop 0
	v_mul_f32_e32 v66, v67, v68
	v_mov_b32_e32 v41, v66
	v_and_b32_sdwa v66, v43, v204 dst_sel:DWORD dst_unused:UNUSED_PAD src0_sel:WORD_1 src1_sel:DWORD
	v_and_b32_sdwa v67, v42, v204 dst_sel:DWORD dst_unused:UNUSED_PAD src0_sel:WORD_1 src1_sel:DWORD
	v_add3_u32 v42, v42, v67, s76
	v_add3_u32 v43, v43, v66, s76
	v_and_b32_sdwa v66, v41, v204 dst_sel:DWORD dst_unused:UNUSED_PAD src0_sel:WORD_1 src1_sel:DWORD
	v_and_b32_sdwa v67, v40, v204 dst_sel:DWORD dst_unused:UNUSED_PAD src0_sel:WORD_1 src1_sel:DWORD
	v_add3_u32 v41, v41, v66, s76
	v_add3_u32 v40, v40, v67, s76
	v_and_b32_e32 v41, 0xffff0000, v41
	v_and_b32_e32 v40, 0xffff0000, v40
	v_pk_mul_f32 v[66:67], v[26:27], v[48:49]
	v_or_b32_sdwa v41, v41, v43 dst_sel:DWORD dst_unused:UNUSED_PAD src0_sel:DWORD src1_sel:WORD_1
	v_or_b32_sdwa v40, v40, v42 dst_sel:DWORD dst_unused:UNUSED_PAD src0_sel:DWORD src1_sel:WORD_1
	v_pk_mul_f32 v[42:43], v[24:25], v[50:51]
	v_pk_fma_f32 v[52:53], v[2:3], v[52:53], v[66:67]
	v_pk_fma_f32 v[42:43], v[0:1], v[54:55], v[42:43]
	v_pk_fma_f32 v[52:53], v[10:11], v[44:45], v[52:53]
	v_pk_fma_f32 v[42:43], v[8:9], v[46:47], v[42:43]
	v_pk_add_f32 v[52:53], v[6:7], v[52:53]
	v_pk_add_f32 v[42:43], v[4:5], v[42:43]
	v_mul_f32_e32 v55, 0xbfb8aa3b, v52
	v_mul_f32_e32 v54, 0xbfb8aa3b, v42
	v_exp_f32_e32 v66, v55
	v_mul_f32_e32 v55, 0xbfb8aa3b, v43
	v_exp_f32_e32 v54, v54
	v_exp_f32_e32 v55, v55
	s_nop 0
	v_pk_add_f32 v[54:55], v[54:55], 1.0 op_sel_hi:[1,0]
	s_nop 0
	s_nop 0
	v_rcp_f32_e32 v68, v54
	s_nop 0
	s_nop 0
	s_nop 0
	s_nop 0
	s_nop 0
	s_nop 0
	s_nop 0
	s_nop 0
	v_mul_f32_e32 v67, v42, v68
	v_mov_b32_e32 v54, v67
	s_nop 0
	v_rcp_f32_e32 v67, v55
	s_nop 0
	s_nop 0
	s_nop 0
	s_nop 0
	s_nop 0
	s_nop 0
	s_nop 0
	s_nop 0
	v_mul_f32_e32 v42, v43, v67
	v_mov_b32_e32 v55, v42
	v_mul_f32_e32 v42, 0xbfb8aa3b, v53
	v_exp_f32_e32 v67, v42
	s_nop 0
	v_pk_add_f32 v[42:43], v[66:67], 1.0 op_sel_hi:[1,0]
	s_nop 0
	s_nop 0
	v_rcp_f32_e32 v67, v42
	s_nop 0
	s_nop 0
	s_nop 0
	s_nop 0
	s_nop 0
	s_nop 0
	s_nop 0
	s_nop 0
	v_mul_f32_e32 v66, v52, v67
	v_mov_b32_e32 v42, v66
	s_nop 0
	v_rcp_f32_e32 v66, v43
	s_nop 0
	s_nop 0
	s_nop 0
	s_nop 0
	s_nop 0
	s_nop 0
	s_nop 0
	s_nop 0
	v_mul_f32_e32 v52, v53, v66
	v_mov_b32_e32 v43, v52
	v_and_b32_sdwa v53, v54, v204 dst_sel:DWORD dst_unused:UNUSED_PAD src0_sel:WORD_1 src1_sel:DWORD
	v_and_b32_sdwa v52, v55, v204 dst_sel:DWORD dst_unused:UNUSED_PAD src0_sel:WORD_1 src1_sel:DWORD
	v_add3_u32 v53, v54, v53, s76
	v_and_b32_sdwa v54, v43, v204 dst_sel:DWORD dst_unused:UNUSED_PAD src0_sel:WORD_1 src1_sel:DWORD
	v_add3_u32 v52, v55, v52, s76
	v_and_b32_sdwa v55, v42, v204 dst_sel:DWORD dst_unused:UNUSED_PAD src0_sel:WORD_1 src1_sel:DWORD
	v_add3_u32 v43, v43, v54, s76
	v_add3_u32 v42, v42, v55, s76
	v_and_b32_e32 v43, 0xffff0000, v43
	v_and_b32_e32 v42, 0xffff0000, v42
	v_or_b32_sdwa v43, v43, v52 dst_sel:DWORD dst_unused:UNUSED_PAD src0_sel:DWORD src1_sel:WORD_1
	v_add_co_u32_e32 v52, vcc, 0x2000, v64
	v_or_b32_sdwa v42, v42, v53 dst_sel:DWORD dst_unused:UNUSED_PAD src0_sel:DWORD src1_sel:WORD_1
	s_nop 0
	v_addc_co_u32_e32 v53, vcc, 0, v65, vcc
	s_and_b64 vcc, exec, s[0:1]
	global_store_dwordx4 v[52:53], v[40:43], off offset:2048
	s_cbranch_vccnz .LBB0_841
	v_add_u32_e32 v52, v176, v179
	ds_write_b128 v52, v[40:43] offset:2640
; DI u32 pack2(float a, float b) { return (u32)f2bf(a) | ((u32)f2bf(b) << 16); }
; DI float silu_f(float x) { return x / (1.f + __expf(-x)); }
; DI void phase_prep(const Params& p, int l, int bid, int nblk, char* smem) {
;     ...
;       for (int k = 0; k < 8; ++k) {
;         unpack8(raw[k + 2], xp);
;         float o[8];
; #pragma unroll
;         for (int e = 0; e < 8; ++e) {
;           o[e] = silu_f(w0[e] * xm[e] + w1[e] * x0[e] + w2[e] * xp[e] + bb[e]);
;           xm[e] = x0[e]; x0[e] = xp[e];
;         }
;         uint4 ov = {pack2(o[0], o[1]), pack2(o[2], o[3]), pack2(o[4], o[5]), pack2(o[6], o[7])};
;         *(uint4*)&XBCA[(rbase + pfirst + k) * 1024 + col] = ov;
;         if (pass < 5) *(uint4*)&tile[(pg * 8 + k) * 264 + cg8] = ov;
;       }
.LBB0_841:
	v_lshlrev_b32_e32 v52, 16, v36
	v_and_b32_e32 v43, 0xffff0000, v37
	v_and_b32_e32 v42, 0xffff0000, v36
	v_lshlrev_b32_e32 v53, 16, v37
	v_pk_mul_f32 v[36:37], v[28:29], v[58:59]
	v_and_b32_e32 v41, 0xffff0000, v39
	v_pk_fma_f32 v[36:37], v[12:13], v[62:63], v[36:37]
	v_pk_mul_f32 v[62:63], v[30:31], v[56:57]
	v_pk_fma_f32 v[36:37], v[20:21], v[52:53], v[36:37]
	v_pk_fma_f32 v[60:61], v[14:15], v[60:61], v[62:63]
	v_lshlrev_b32_e32 v55, 16, v39
	v_pk_fma_f32 v[60:61], v[22:23], v[42:43], v[60:61]
	v_pk_add_f32 v[36:37], v[16:17], v[36:37]
	v_pk_add_f32 v[60:61], v[18:19], v[60:61]
	v_lshlrev_b32_e32 v54, 16, v38
	v_mul_f32_e32 v39, 0xbfb8aa3b, v60
	v_and_b32_e32 v40, 0xffff0000, v38
	v_mul_f32_e32 v38, 0xbfb8aa3b, v36
	v_exp_f32_e32 v62, v39
	v_mul_f32_e32 v39, 0xbfb8aa3b, v37
	v_exp_f32_e32 v38, v38
	v_exp_f32_e32 v39, v39
	s_nop 0
	v_pk_add_f32 v[38:39], v[38:39], 1.0 op_sel_hi:[1,0]
	s_nop 0
	s_nop 0
	v_rcp_f32_e32 v66, v38
	s_nop 0
	s_nop 0
	s_nop 0
	s_nop 0
	s_nop 0
	s_nop 0
	s_nop 0
	s_nop 0
	v_mul_f32_e32 v63, v36, v66
	v_mov_b32_e32 v38, v63
	s_nop 0
	v_rcp_f32_e32 v63, v39
	s_nop 0
	s_nop 0
	s_nop 0
	s_nop 0
	s_nop 0
	s_nop 0
	s_nop 0
	s_nop 0
	v_mul_f32_e32 v36, v37, v63
	v_mov_b32_e32 v39, v36
	v_mul_f32_e32 v36, 0xbfb8aa3b, v61
	v_exp_f32_e32 v63, v36
	s_nop 0
	v_pk_add_f32 v[36:37], v[62:63], 1.0 op_sel_hi:[1,0]
	s_nop 0
	s_nop 0
	v_rcp_f32_e32 v63, v36
	s_nop 0
	s_nop 0
	s_nop 0
	s_nop 0
	s_nop 0
	s_nop 0
	s_nop 0
	s_nop 0
	v_mul_f32_e32 v62, v60, v63
	v_mov_b32_e32 v36, v62
	s_nop 0
	v_rcp_f32_e32 v62, v37
	s_nop 0
	s_nop 0
	s_nop 0
	s_nop 0
	s_nop 0
	s_nop 0
	s_nop 0
	s_nop 0
	v_mul_f32_e32 v60, v61, v62
	v_mov_b32_e32 v37, v60
	v_and_b32_sdwa v60, v39, v204 dst_sel:DWORD dst_unused:UNUSED_PAD src0_sel:WORD_1 src1_sel:DWORD
	v_and_b32_sdwa v61, v38, v204 dst_sel:DWORD dst_unused:UNUSED_PAD src0_sel:WORD_1 src1_sel:DWORD
	v_add3_u32 v38, v38, v61, s76
	v_add3_u32 v39, v39, v60, s76
	v_and_b32_sdwa v60, v37, v204 dst_sel:DWORD dst_unused:UNUSED_PAD src0_sel:WORD_1 src1_sel:DWORD
	v_and_b32_sdwa v61, v36, v204 dst_sel:DWORD dst_unused:UNUSED_PAD src0_sel:WORD_1 src1_sel:DWORD
	v_add3_u32 v37, v37, v60, s76
	v_add3_u32 v36, v36, v61, s76
	v_and_b32_e32 v37, 0xffff0000, v37
	v_and_b32_e32 v36, 0xffff0000, v36
	v_pk_mul_f32 v[60:61], v[26:27], v[44:45]
	v_or_b32_sdwa v37, v37, v39 dst_sel:DWORD dst_unused:UNUSED_PAD src0_sel:DWORD src1_sel:WORD_1
	v_or_b32_sdwa v36, v36, v38 dst_sel:DWORD dst_unused:UNUSED_PAD src0_sel:DWORD src1_sel:WORD_1
	v_pk_mul_f32 v[38:39], v[24:25], v[46:47]
	v_pk_fma_f32 v[48:49], v[2:3], v[48:49], v[60:61]
	v_pk_fma_f32 v[38:39], v[0:1], v[50:51], v[38:39]
	v_pk_fma_f32 v[48:49], v[10:11], v[40:41], v[48:49]
	v_pk_fma_f32 v[38:39], v[8:9], v[54:55], v[38:39]
	v_pk_add_f32 v[48:49], v[6:7], v[48:49]
	v_pk_add_f32 v[38:39], v[4:5], v[38:39]
	v_mul_f32_e32 v51, 0xbfb8aa3b, v48
	v_mul_f32_e32 v50, 0xbfb8aa3b, v38
	v_exp_f32_e32 v60, v51
	v_mul_f32_e32 v51, 0xbfb8aa3b, v39
	v_exp_f32_e32 v50, v50
	v_exp_f32_e32 v51, v51
	s_nop 0
	v_pk_add_f32 v[50:51], v[50:51], 1.0 op_sel_hi:[1,0]
	s_nop 0
	s_nop 0
	v_rcp_f32_e32 v62, v50
	s_nop 0
	s_nop 0
	s_nop 0
	s_nop 0
	s_nop 0
	s_nop 0
	s_nop 0
	s_nop 0
	v_mul_f32_e32 v61, v38, v62
	v_mov_b32_e32 v50, v61
	s_nop 0
	v_rcp_f32_e32 v61, v51
	s_nop 0
	s_nop 0
	s_nop 0
	s_nop 0
	s_nop 0
	s_nop 0
	s_nop 0
	s_nop 0
	v_mul_f32_e32 v38, v39, v61
	v_mov_b32_e32 v51, v38
	v_mul_f32_e32 v38, 0xbfb8aa3b, v49
	v_exp_f32_e32 v61, v38
	s_nop 0
	v_pk_add_f32 v[38:39], v[60:61], 1.0 op_sel_hi:[1,0]
	s_nop 0
	s_nop 0
	v_rcp_f32_e32 v61, v38
	s_nop 0
	s_nop 0
	s_nop 0
	s_nop 0
	s_nop 0
	s_nop 0
	s_nop 0
	s_nop 0
	v_mul_f32_e32 v60, v48, v61
	v_mov_b32_e32 v38, v60
	s_nop 0
	v_rcp_f32_e32 v60, v39
	s_nop 0
	s_nop 0
	s_nop 0
	s_nop 0
	s_nop 0
	s_nop 0
	s_nop 0
	s_nop 0
	v_mul_f32_e32 v48, v49, v60
	v_mov_b32_e32 v39, v48
	v_and_b32_sdwa v49, v50, v204 dst_sel:DWORD dst_unused:UNUSED_PAD src0_sel:WORD_1 src1_sel:DWORD
	v_and_b32_sdwa v48, v51, v204 dst_sel:DWORD dst_unused:UNUSED_PAD src0_sel:WORD_1 src1_sel:DWORD
	v_add3_u32 v49, v50, v49, s76
	v_and_b32_sdwa v50, v39, v204 dst_sel:DWORD dst_unused:UNUSED_PAD src0_sel:WORD_1 src1_sel:DWORD
	v_add3_u32 v48, v51, v48, s76
	v_and_b32_sdwa v51, v38, v204 dst_sel:DWORD dst_unused:UNUSED_PAD src0_sel:WORD_1 src1_sel:DWORD
	v_add3_u32 v39, v39, v50, s76
	v_add3_u32 v38, v38, v51, s76
	v_and_b32_e32 v39, 0xffff0000, v39
	v_and_b32_e32 v38, 0xffff0000, v38
	v_or_b32_sdwa v39, v39, v48 dst_sel:DWORD dst_unused:UNUSED_PAD src0_sel:DWORD src1_sel:WORD_1
	v_add_co_u32_e32 v48, vcc, 0x3000, v64
	v_or_b32_sdwa v38, v38, v49 dst_sel:DWORD dst_unused:UNUSED_PAD src0_sel:DWORD src1_sel:WORD_1
	s_nop 0
	v_addc_co_u32_e32 v49, vcc, 0, v65, vcc
	s_and_b64 vcc, exec, s[0:1]
	global_store_dwordx4 v[48:49], v[36:39], off
	s_cbranch_vccnz .LBB0_843
	v_add_u32_e32 v48, v176, v179
	ds_write_b128 v48, v[36:39] offset:3168

; DI int TID() { int t = threadIdx.x; asm volatile("" : "+v"(t)); return t; }
; DI u32 pack2(float a, float b) { return (u32)f2bf(a) | ((u32)f2bf(b) << 16); }
; DI float bflo(u32 v) { return __uint_as_float(v << 16); }
; DI float bfhi(u32 v) { return __uint_as_float(v & 0xffff0000u); }
; DI float silu_f(float x) { return x / (1.f + __expf(-x)); }
; DI void phase_ssd_combine(const Params& p, int l, int bid, int nblk) {
;   const int lane = TID() & 63, w = TID() >> 6;
;   const u16* YF = WSP(const u16, OFF_PXBC);
;   const u16* YB = YF + (size_t)ROWS * 512;
;   const u16* XBCA = WSP(const u16, OFF_XBCA);
;   const u16* PZ = WSP(const u16, OFF_PZ);
;   u16* YM = WSP(u16, OFF_ACT);
;   const float* ng = p.in[I_SNG] + l * 512;
;   const int c0 = lane * 8;
;   const float dsk = p.in[I_SD][l * 8 + (c0 >> 6)];
;   for (int row = bid * 4 + w; row < ROWS; row += nblk * 4) {
;     const int pos = row % TPB;
;     if (l == 1 && pos < CTXL) continue;
;     const uint4 vf = *(const uint4*)(YF + (size_t)row * 512 + c0);
;     const uint4 vb = *(const uint4*)(YB + (size_t)row * 512 + c0);
;     const uint4 vx = *(const uint4*)(XBCA + (size_t)row * 1024 + c0);
;     const uint4 vz = *(const uint4*)(PZ + (size_t)row * 512 + c0);
;     const u32 af_[4] = {vf.x, vf.y, vf.z, vf.w}, ab_[4] = {vb.x, vb.y, vb.z, vb.w};
;     const u32 ax_[4] = {vx.x, vx.y, vx.z, vx.w}, az_[4] = {vz.x, vz.y, vz.z, vz.w};
;     float y[8];
;     float ss = 0.f;
; #pragma unroll
;     for (int i = 0; i < 4; ++i) {
;       const float y0 = bflo(af_[i]) + bflo(ab_[i]) + dsk * bflo(ax_[i]);
;       const float y1 = bfhi(af_[i]) + bfhi(ab_[i]) + dsk * bfhi(ax_[i]);
;       y[2 * i] = y0 * silu_f(bflo(az_[i]));
;       y[2 * i + 1] = y1 * silu_f(bfhi(az_[i]));
;       ss += y[2 * i] * y[2 * i] + y[2 * i + 1] * y[2 * i + 1];
;     }
; #pragma unroll
;     for (int o = 16; o >= 1; o >>= 1) ss += __shfl_xor(ss, o);
;     const float rs = rsqrtf(ss * (1.f / 256.f) + EPSF);
;     float o8[8];
; #pragma unroll
;     for (int i = 0; i < 8; ++i) o8[i] = y[i] * rs * ng[c0 + i];
;     uint4 o = {pack2(o8[0], o8[1]), pack2(o8[2], o8[3]), pack2(o8[4], o8[5]), pack2(o8[6], o8[7])};
;     *(uint4*)&YM[(size_t)row * 1024 + 256 + c0] = o;
.LBB0_1203:
	s_or_b64 exec, exec, s[0:1]
	v_mov_b32_e32 v1, v218
	s_waitcnt lgkmcnt(0)
	v_mov_b32_e32 v0, v218
	s_barrier
	s_mov_b64 s[36:37], exec
	v_lshrrev_b32_e32 v4, 6, v218
	v_readlane_b32 s19, v255, 58
	v_and_b32_e32 v10, 63, v218
	v_readlane_b32 s50, v254, 41
	v_readlane_b32 s51, v254, 42
	v_readlane_b32 s56, v254, 43
	v_readlane_b32 s57, v254, 44
	v_readfirstlane_b32 s22, v4
	s_add_i32 s19, s19, s22
	s_mov_b32 s23, 99
	s_mov_b32 s25, 99
	s_movk_i32 s26, 18
	s_cmp_eq_u64 s[70:71], 0
	s_cbranch_scc1 .Lcmb_noskip
	s_lshr_b32 s23, s19, 8
	s_add_i32 s25, s23, 9
	s_movk_i32 s26, 16
.Lcmb_noskip:
	s_lshl_b32 s16, s24, 11
	s_add_u32 s56, s56, s16
	s_addc_u32 s57, s57, 0
	v_lshrrev_b32_e32 v5, 3, v10
	v_lshl_add_u32 v5, s24, 3, v5
	v_lshlrev_b32_e32 v5, 2, v5
	v_lshlrev_b32_e32 v6, 5, v10
	global_load_dword v24, v5, s[50:51]
	global_load_dwordx4 v[16:19], v6, s[56:57]
	global_load_dwordx4 v[20:23], v6, s[56:57] offset:16
	v_lshlrev_b32_e32 v4, 4, v10
	v_xor_b32_e32 v5, 16, v10
	v_lshlrev_b32_e32 v5, 2, v5
	s_mov_b32 s27, 0
	s_cmp_ge_u32 s27, s23
	s_addc_u32 s44, s27, 0
	s_cmp_ge_u32 s44, s25
	s_addc_u32 s44, s44, 0
	s_lshl_b32 s44, s44, 11
	s_add_i32 s44, s44, s19
	s_lshl_b32 s16, s44, 10
	s_lshl_b32 s17, s44, 11
	s_add_u32 s30, s96, s16
	s_addc_u32 s31, s97, 0
	s_add_u32 s48, s30, 0x3600000
	s_addc_u32 s49, s31, 0
	s_add_u32 s30, s30, 0x5a00000
	s_addc_u32 s31, s31, 0
	s_add_u32 s38, s30, 0x2400000
	s_addc_u32 s39, s31, 0
	s_add_u32 s66, s96, s17
	s_addc_u32 s67, s97, 0
	s_add_u32 s66, s66, 0xea00000
	s_addc_u32 s67, s67, 0
	s_add_u32 s80, s6, s17
	s_addc_u32 s81, s7, 0
	global_load_dwordx4 v[32:35], v4, s[30:31]
	global_load_dwordx4 v[36:39], v4, s[38:39]
	global_load_dwordx4 v[40:43], v4, s[66:67]
	global_load_dwordx4 v[44:47], v4, s[48:49]
	s_mov_b32 s28, 1
	s_cmp_ge_u32 s28, s23
	s_addc_u32 s44, s28, 0
	s_cmp_ge_u32 s44, s25
	s_addc_u32 s44, s44, 0
	s_lshl_b32 s44, s44, 11
	s_add_i32 s44, s44, s19
	s_lshl_b32 s16, s44, 10
	s_lshl_b32 s17, s44, 11
	s_add_u32 s30, s96, s16
	s_addc_u32 s31, s97, 0
	s_add_u32 s48, s30, 0x3600000
	s_addc_u32 s49, s31, 0
	s_add_u32 s30, s30, 0x5a00000
	s_addc_u32 s31, s31, 0
	s_add_u32 s38, s30, 0x2400000
	s_addc_u32 s39, s31, 0
	s_add_u32 s66, s96, s17
	s_addc_u32 s67, s97, 0
	s_add_u32 s66, s66, 0xea00000
	s_addc_u32 s67, s67, 0
	s_add_u32 s82, s6, s17
	s_addc_u32 s83, s7, 0
	global_load_dwordx4 v[48:51], v4, s[30:31]
	global_load_dwordx4 v[52:55], v4, s[38:39]
	global_load_dwordx4 v[56:59], v4, s[66:67]
	global_load_dwordx4 v[60:63], v4, s[48:49]
	s_waitcnt vmcnt(4)
.Lcmb_top:
	s_waitcnt vmcnt(5)
	v_lshlrev_b32_e32 v64, 16, v32
	v_and_b32_e32 v65, 0xffff0000, v32
	v_lshlrev_b32_e32 v66, 16, v33
	v_and_b32_e32 v67, 0xffff0000, v33
	v_lshlrev_b32_e32 v68, 16, v34
	v_and_b32_e32 v69, 0xffff0000, v34
	v_lshlrev_b32_e32 v70, 16, v35
	v_and_b32_e32 v71, 0xffff0000, v35
	v_lshlrev_b32_e32 v80, 16, v36
	v_and_b32_e32 v81, 0xffff0000, v36
	v_lshlrev_b32_e32 v82, 16, v37
	v_and_b32_e32 v83, 0xffff0000, v37
	v_lshlrev_b32_e32 v84, 16, v38
	v_and_b32_e32 v85, 0xffff0000, v38
	v_lshlrev_b32_e32 v86, 16, v39
	v_and_b32_e32 v87, 0xffff0000, v39
	v_add_f32_e32 v64, v64, v80
	v_add_f32_e32 v65, v65, v81
	v_add_f32_e32 v66, v66, v82
	v_add_f32_e32 v67, v67, v83
	v_add_f32_e32 v68, v68, v84
	v_add_f32_e32 v69, v69, v85
	v_add_f32_e32 v70, v70, v86
	v_add_f32_e32 v71, v71, v87
	v_lshlrev_b32_e32 v80, 16, v40
	v_and_b32_e32 v81, 0xffff0000, v40
	v_lshlrev_b32_e32 v82, 16, v41
	v_and_b32_e32 v83, 0xffff0000, v41
	v_lshlrev_b32_e32 v84, 16, v42
	v_and_b32_e32 v85, 0xffff0000, v42
	v_lshlrev_b32_e32 v86, 16, v43
	v_and_b32_e32 v87, 0xffff0000, v43
	v_fmac_f32_e32 v64, v24, v80
	v_fmac_f32_e32 v65, v24, v81
	v_fmac_f32_e32 v66, v24, v82
	v_fmac_f32_e32 v67, v24, v83
	v_fmac_f32_e32 v68, v24, v84
	v_fmac_f32_e32 v69, v24, v85
	v_fmac_f32_e32 v70, v24, v86
	v_fmac_f32_e32 v71, v24, v87
	v_lshlrev_b32_e32 v72, 16, v44
	v_and_b32_e32 v73, 0xffff0000, v44
	v_lshlrev_b32_e32 v74, 16, v45
	v_and_b32_e32 v75, 0xffff0000, v45
	v_lshlrev_b32_e32 v76, 16, v46
	v_and_b32_e32 v77, 0xffff0000, v46
	v_lshlrev_b32_e32 v78, 16, v47
	v_and_b32_e32 v79, 0xffff0000, v47
	v_mul_f32_e32 v80, 0xbfb8aa3b, v72
	v_mul_f32_e32 v81, 0xbfb8aa3b, v73
	v_mul_f32_e32 v82, 0xbfb8aa3b, v74
	v_mul_f32_e32 v83, 0xbfb8aa3b, v75
	v_mul_f32_e32 v84, 0xbfb8aa3b, v76
	v_mul_f32_e32 v85, 0xbfb8aa3b, v77
	v_mul_f32_e32 v86, 0xbfb8aa3b, v78
	v_mul_f32_e32 v87, 0xbfb8aa3b, v79
	v_exp_f32_e32 v80, v80
	v_exp_f32_e32 v81, v81
	v_exp_f32_e32 v82, v82
	v_exp_f32_e32 v83, v83
	v_exp_f32_e32 v84, v84
	v_exp_f32_e32 v85, v85
	v_exp_f32_e32 v86, v86
	v_exp_f32_e32 v87, v87
	v_add_f32_e32 v80, 1.0, v80
	v_add_f32_e32 v81, 1.0, v81
	v_add_f32_e32 v82, 1.0, v82
	v_add_f32_e32 v83, 1.0, v83
	v_add_f32_e32 v84, 1.0, v84
	v_add_f32_e32 v85, 1.0, v85
	v_add_f32_e32 v86, 1.0, v86
	v_add_f32_e32 v87, 1.0, v87
	v_rcp_f32_e32 v80, v80
	v_rcp_f32_e32 v81, v81
	v_rcp_f32_e32 v82, v82
	v_rcp_f32_e32 v83, v83
	v_rcp_f32_e32 v84, v84
	v_rcp_f32_e32 v85, v85
	v_rcp_f32_e32 v86, v86
	v_rcp_f32_e32 v87, v87
	v_mul_f32_e32 v72, v72, v80
	v_mul_f32_e32 v73, v73, v81
	v_mul_f32_e32 v74, v74, v82
	v_mul_f32_e32 v75, v75, v83
	v_mul_f32_e32 v76, v76, v84
	v_mul_f32_e32 v77, v77, v85
	v_mul_f32_e32 v78, v78, v86
	v_mul_f32_e32 v79, v79, v87
	v_mul_f32_e32 v64, v64, v72
	v_mul_f32_e32 v65, v65, v73
	v_mul_f32_e32 v66, v66, v74
	v_mul_f32_e32 v67, v67, v75
	v_mul_f32_e32 v68, v68, v76
	v_mul_f32_e32 v69, v69, v77
	v_mul_f32_e32 v70, v70, v78
	v_mul_f32_e32 v71, v71, v79
	v_mul_f32_e32 v7, v64, v64
	v_fmac_f32_e32 v7, v65, v65
	v_fmac_f32_e32 v7, v66, v66
	v_fmac_f32_e32 v7, v67, v67
	v_fmac_f32_e32 v7, v68, v68
	v_fmac_f32_e32 v7, v69, v69
	v_fmac_f32_e32 v7, v70, v70
	v_fmac_f32_e32 v7, v71, v71
	s_nop 1
	v_add_f32_dpp v7, v7, v7 quad_perm:[1,0,3,2] row_mask:0xf bank_mask:0xf
	s_nop 1
	v_add_f32_dpp v7, v7, v7 quad_perm:[2,3,0,1] row_mask:0xf bank_mask:0xf
	s_nop 1
	v_add_f32_dpp v7, v7, v7 row_half_mirror row_mask:0xf bank_mask:0xf
	s_nop 1
	v_add_f32_dpp v7, v7, v7 row_mirror row_mask:0xf bank_mask:0xf
	s_nop 1
	ds_bpermute_b32 v8, v5, v7
	s_waitcnt lgkmcnt(0)
; DI u32 pack2(float a, float b) { return (u32)f2bf(a) | ((u32)f2bf(b) << 16); }
; DI float bflo(u32 v) { return __uint_as_float(v << 16); }
; DI float bfhi(u32 v) { return __uint_as_float(v & 0xffff0000u); }
; DI float silu_f(float x) { return x / (1.f + __expf(-x)); }
; DI void phase_ssd_combine(const Params& p, int l, int bid, int nblk) {
;     ...
;   for (int row = bid * 4 + w; row < ROWS; row += nblk * 4) {
;     const int pos = row % TPB;
;     if (l == 1 && pos < CTXL) continue;
;     const uint4 vf = *(const uint4*)(YF + (size_t)row * 512 + c0);
;     const uint4 vb = *(const uint4*)(YB + (size_t)row * 512 + c0);
;     const uint4 vx = *(const uint4*)(XBCA + (size_t)row * 1024 + c0);
;     const uint4 vz = *(const uint4*)(PZ + (size_t)row * 512 + c0);
;     const u32 af_[4] = {vf.x, vf.y, vf.z, vf.w}, ab_[4] = {vb.x, vb.y, vb.z, vb.w};
;     const u32 ax_[4] = {vx.x, vx.y, vx.z, vx.w}, az_[4] = {vz.x, vz.y, vz.z, vz.w};
;     float y[8];
;     float ss = 0.f;
; #pragma unroll
;     for (int i = 0; i < 4; ++i) {
;       const float y0 = bflo(af_[i]) + bflo(ab_[i]) + dsk * bflo(ax_[i]);
;       const float y1 = bfhi(af_[i]) + bfhi(ab_[i]) + dsk * bfhi(ax_[i]);
;       y[2 * i] = y0 * silu_f(bflo(az_[i]));
;       y[2 * i + 1] = y1 * silu_f(bfhi(az_[i]));
;       ss += y[2 * i] * y[2 * i] + y[2 * i + 1] * y[2 * i + 1];
;     }
; #pragma unroll
;     for (int o = 16; o >= 1; o >>= 1) ss += __shfl_xor(ss, o);
;     const float rs = rsqrtf(ss * (1.f / 256.f) + EPSF);
;     float o8[8];
; #pragma unroll
;     for (int i = 0; i < 8; ++i) o8[i] = y[i] * rs * ng[c0 + i];
;     uint4 o = {pack2(o8[0], o8[1]), pack2(o8[2], o8[3]), pack2(o8[4], o8[5]), pack2(o8[6], o8[7])};
;     *(uint4*)&YM[(size_t)row * 1024 + 256 + c0] = o;
	v_add_f32_e32 v7, v7, v8
	v_mov_b32_e32 v8, 0x358637bd
	v_fmac_f32_e32 v8, 0x3b800000, v7
	v_rsq_f32_e32 v8, v8
	s_nop 0
	v_mul_f32_e32 v64, v64, v8
	v_mul_f32_e32 v65, v65, v8
	v_mul_f32_e32 v66, v66, v8
	v_mul_f32_e32 v67, v67, v8
	v_mul_f32_e32 v68, v68, v8
	v_mul_f32_e32 v69, v69, v8
	v_mul_f32_e32 v70, v70, v8
	v_mul_f32_e32 v71, v71, v8
	v_mul_f32_e32 v64, v64, v16
	v_mul_f32_e32 v65, v65, v17
	v_mul_f32_e32 v66, v66, v18
	v_mul_f32_e32 v67, v67, v19
	v_mul_f32_e32 v68, v68, v20
	v_mul_f32_e32 v69, v69, v21
	v_mul_f32_e32 v70, v70, v22
	v_mul_f32_e32 v71, v71, v23
	v_cvt_pk_bf16_f32 v88, v64, v65
	v_cvt_pk_bf16_f32 v89, v66, v67
	v_cvt_pk_bf16_f32 v90, v68, v69
	v_cvt_pk_bf16_f32 v91, v70, v71
	s_nop 0
	global_store_dwordx4 v4, v[88:91], s[80:81] offset:512
	s_add_i32 s28, s27, 2
	s_cmp_lt_u32 s28, s26
	s_cselect_b32 s28, s28, 0
	s_cmp_ge_u32 s28, s23
	s_addc_u32 s44, s28, 0
	s_cmp_ge_u32 s44, s25
	s_addc_u32 s44, s44, 0
	s_lshl_b32 s44, s44, 11
	s_add_i32 s44, s44, s19
	s_lshl_b32 s16, s44, 10
	s_lshl_b32 s17, s44, 11
	s_add_u32 s30, s96, s16
	s_addc_u32 s31, s97, 0
	s_add_u32 s48, s30, 0x3600000
	s_addc_u32 s49, s31, 0
	s_add_u32 s30, s30, 0x5a00000
	s_addc_u32 s31, s31, 0
	s_add_u32 s38, s30, 0x2400000
	s_addc_u32 s39, s31, 0
	s_add_u32 s66, s96, s17
	s_addc_u32 s67, s97, 0
	s_add_u32 s66, s66, 0xea00000
	s_addc_u32 s67, s67, 0
	s_add_u32 s80, s6, s17
	s_addc_u32 s81, s7, 0
	global_load_dwordx4 v[32:35], v4, s[30:31]
	global_load_dwordx4 v[36:39], v4, s[38:39]
	global_load_dwordx4 v[40:43], v4, s[66:67]
	global_load_dwordx4 v[44:47], v4, s[48:49]
	s_waitcnt vmcnt(5)
	v_lshlrev_b32_e32 v64, 16, v48
	v_and_b32_e32 v65, 0xffff0000, v48
	v_lshlrev_b32_e32 v66, 16, v49
	v_and_b32_e32 v67, 0xffff0000, v49
	v_lshlrev_b32_e32 v68, 16, v50
	v_and_b32_e32 v69, 0xffff0000, v50
	v_lshlrev_b32_e32 v70, 16, v51
	v_and_b32_e32 v71, 0xffff0000, v51
	v_lshlrev_b32_e32 v80, 16, v52
	v_and_b32_e32 v81, 0xffff0000, v52
	v_lshlrev_b32_e32 v82, 16, v53
	v_and_b32_e32 v83, 0xffff0000, v53
	v_lshlrev_b32_e32 v84, 16, v54
	v_and_b32_e32 v85, 0xffff0000, v54
	v_lshlrev_b32_e32 v86, 16, v55
	v_and_b32_e32 v87, 0xffff0000, v55
	v_add_f32_e32 v64, v64, v80
	v_add_f32_e32 v65, v65, v81
	v_add_f32_e32 v66, v66, v82
	v_add_f32_e32 v67, v67, v83
	v_add_f32_e32 v68, v68, v84
	v_add_f32_e32 v69, v69, v85
	v_add_f32_e32 v70, v70, v86
	v_add_f32_e32 v71, v71, v87
	v_lshlrev_b32_e32 v80, 16, v56
	v_and_b32_e32 v81, 0xffff0000, v56
	v_lshlrev_b32_e32 v82, 16, v57
	v_and_b32_e32 v83, 0xffff0000, v57
	v_lshlrev_b32_e32 v84, 16, v58
	v_and_b32_e32 v85, 0xffff0000, v58
	v_lshlrev_b32_e32 v86, 16, v59
	v_and_b32_e32 v87, 0xffff0000, v59
	v_fmac_f32_e32 v64, v24, v80
	v_fmac_f32_e32 v65, v24, v81
	v_fmac_f32_e32 v66, v24, v82
	v_fmac_f32_e32 v67, v24, v83
	v_fmac_f32_e32 v68, v24, v84
	v_fmac_f32_e32 v69, v24, v85
	v_fmac_f32_e32 v70, v24, v86
	v_fmac_f32_e32 v71, v24, v87
	v_lshlrev_b32_e32 v72, 16, v60
	v_and_b32_e32 v73, 0xffff0000, v60
	v_lshlrev_b32_e32 v74, 16, v61
	v_and_b32_e32 v75, 0xffff0000, v61
	v_lshlrev_b32_e32 v76, 16, v62
	v_and_b32_e32 v77, 0xffff0000, v62
	v_lshlrev_b32_e32 v78, 16, v63
	v_and_b32_e32 v79, 0xffff0000, v63
	v_mul_f32_e32 v80, 0xbfb8aa3b, v72
	v_mul_f32_e32 v81, 0xbfb8aa3b, v73
	v_mul_f32_e32 v82, 0xbfb8aa3b, v74
	v_mul_f32_e32 v83, 0xbfb8aa3b, v75
	v_mul_f32_e32 v84, 0xbfb8aa3b, v76
	v_mul_f32_e32 v85, 0xbfb8aa3b, v77
	v_mul_f32_e32 v86, 0xbfb8aa3b, v78
	v_mul_f32_e32 v87, 0xbfb8aa3b, v79
	v_exp_f32_e32 v80, v80
	v_exp_f32_e32 v81, v81
	v_exp_f32_e32 v82, v82
	v_exp_f32_e32 v83, v83
	v_exp_f32_e32 v84, v84
	v_exp_f32_e32 v85, v85
	v_exp_f32_e32 v86, v86
	v_exp_f32_e32 v87, v87
	v_add_f32_e32 v80, 1.0, v80
	v_add_f32_e32 v81, 1.0, v81
	v_add_f32_e32 v82, 1.0, v82
	v_add_f32_e32 v83, 1.0, v83
	v_add_f32_e32 v84, 1.0, v84
	v_add_f32_e32 v85, 1.0, v85
	v_add_f32_e32 v86, 1.0, v86
	v_add_f32_e32 v87, 1.0, v87
	v_rcp_f32_e32 v80, v80
	v_rcp_f32_e32 v81, v81
	v_rcp_f32_e32 v82, v82
	v_rcp_f32_e32 v83, v83
	v_rcp_f32_e32 v84, v84
	v_rcp_f32_e32 v85, v85
	v_rcp_f32_e32 v86, v86
	v_rcp_f32_e32 v87, v87
	v_mul_f32_e32 v72, v72, v80
	v_mul_f32_e32 v73, v73, v81
	v_mul_f32_e32 v74, v74, v82
	v_mul_f32_e32 v75, v75, v83
	v_mul_f32_e32 v76, v76, v84
	v_mul_f32_e32 v77, v77, v85
	v_mul_f32_e32 v78, v78, v86
	v_mul_f32_e32 v79, v79, v87
	v_mul_f32_e32 v64, v64, v72
	v_mul_f32_e32 v65, v65, v73
	v_mul_f32_e32 v66, v66, v74
	v_mul_f32_e32 v67, v67, v75
	v_mul_f32_e32 v68, v68, v76
	v_mul_f32_e32 v69, v69, v77
	v_mul_f32_e32 v70, v70, v78
	v_mul_f32_e32 v71, v71, v79
	v_mul_f32_e32 v7, v64, v64
	v_fmac_f32_e32 v7, v65, v65
	v_fmac_f32_e32 v7, v66, v66
	v_fmac_f32_e32 v7, v67, v67
	v_fmac_f32_e32 v7, v68, v68
	v_fmac_f32_e32 v7, v69, v69
	v_fmac_f32_e32 v7, v70, v70
	v_fmac_f32_e32 v7, v71, v71
	s_nop 1
	v_add_f32_dpp v7, v7, v7 quad_perm:[1,0,3,2] row_mask:0xf bank_mask:0xf
	s_nop 1
	v_add_f32_dpp v7, v7, v7 quad_perm:[2,3,0,1] row_mask:0xf bank_mask:0xf
	s_nop 1
	v_add_f32_dpp v7, v7, v7 row_half_mirror row_mask:0xf bank_mask:0xf
	s_nop 1
	v_add_f32_dpp v7, v7, v7 row_mirror row_mask:0xf bank_mask:0xf
	s_nop 1
	ds_bpermute_b32 v8, v5, v7
	s_waitcnt lgkmcnt(0)
	v_add_f32_e32 v7, v7, v8
	v_mov_b32_e32 v8, 0x358637bd
	v_fmac_f32_e32 v8, 0x3b800000, v7
	v_rsq_f32_e32 v8, v8
	s_nop 0
	v_mul_f32_e32 v64, v64, v8
	v_mul_f32_e32 v65, v65, v8
	v_mul_f32_e32 v66, v66, v8
	v_mul_f32_e32 v67, v67, v8
	v_mul_f32_e32 v68, v68, v8
	v_mul_f32_e32 v69, v69, v8
	v_mul_f32_e32 v70, v70, v8
	v_mul_f32_e32 v71, v71, v8
	v_mul_f32_e32 v64, v64, v16
	v_mul_f32_e32 v65, v65, v17
	v_mul_f32_e32 v66, v66, v18
	v_mul_f32_e32 v67, v67, v19
	v_mul_f32_e32 v68, v68, v20
	v_mul_f32_e32 v69, v69, v21
	v_mul_f32_e32 v70, v70, v22
	v_mul_f32_e32 v71, v71, v23
	v_cvt_pk_bf16_f32 v88, v64, v65
	v_cvt_pk_bf16_f32 v89, v66, v67
	v_cvt_pk_bf16_f32 v90, v68, v69
	v_cvt_pk_bf16_f32 v91, v70, v71
	s_nop 0
	global_store_dwordx4 v4, v[88:91], s[82:83] offset:512
	s_add_i32 s28, s27, 3
	s_cmp_lt_u32 s28, s26
	s_cselect_b32 s28, s28, 0
	s_cmp_ge_u32 s28, s23
	s_addc_u32 s44, s28, 0
	s_cmp_ge_u32 s44, s25
	s_addc_u32 s44, s44, 0
	s_lshl_b32 s44, s44, 11
	s_add_i32 s44, s44, s19
	s_lshl_b32 s16, s44, 10
	s_lshl_b32 s17, s44, 11
	s_add_u32 s30, s96, s16
	s_addc_u32 s31, s97, 0
	s_add_u32 s48, s30, 0x3600000
	s_addc_u32 s49, s31, 0
	s_add_u32 s30, s30, 0x5a00000
	s_addc_u32 s31, s31, 0
	s_add_u32 s38, s30, 0x2400000
	s_addc_u32 s39, s31, 0
	s_add_u32 s66, s96, s17
	s_addc_u32 s67, s97, 0
	s_add_u32 s66, s66, 0xea00000
	s_addc_u32 s67, s67, 0
	s_add_u32 s82, s6, s17
	s_addc_u32 s83, s7, 0
	global_load_dwordx4 v[48:51], v4, s[30:31]
	global_load_dwordx4 v[52:55], v4, s[38:39]
	global_load_dwordx4 v[56:59], v4, s[66:67]
	global_load_dwordx4 v[60:63], v4, s[48:49]
	s_add_i32 s27, s27, 2
	s_cmp_lt_u32 s27, s26
	s_cbranch_scc1 .Lcmb_top
	s_waitcnt vmcnt(0)

; DI void phase_norm(const Params& p, int l, int which, int bid, int nblk) {
;     ...
;   for (int row = bid * 4 + w; row < ROWS; row += nblk * 4) {
;     const int b = row / TPB, pos = row % TPB;
;     if (which == 1 && l == 1 && pos < CTXL) continue;
;     const float* xr = xrow_ptr(p, from_input, b, pos);
;     const float* mod = WSP(const float, OFF_MOD) + (size_t)(l * 17 + (pos < CTXL ? 16 : b)) * 6144 + which * 3072;
;     float x[16];
; #pragma unroll
;     for (int hh = 0; hh < 2; ++hh) {
;       const float4 a = *(const float4*)(xr + hh * 512 + lane * 8);
;       const float4 c = *(const float4*)(xr + hh * 512 + lane * 8 + 4);
;       x[hh * 8 + 0] = a.x; x[hh * 8 + 1] = a.y; x[hh * 8 + 2] = a.z; x[hh * 8 + 3] = a.w;
;       x[hh * 8 + 4] = c.x; x[hh * 8 + 5] = c.y; x[hh * 8 + 6] = c.z; x[hh * 8 + 7] = c.w;
;     }
.Ln2_1_ptr:
	s_mul_i32 s46, s46, 0x6000
	s_add_u32 s36, s96, 0x1be07000
	s_addc_u32 s37, s97, 0
	s_add_u32 s36, s36, s46
	s_addc_u32 s37, s37, 0
	s_add_u32 s38, s36, 0x1000
	s_addc_u32 s39, s37, 0
	s_lshl_b32 s17, s44, 11
	s_add_u32 s50, s6, s17
	s_addc_u32 s51, s7, 0
	global_load_dwordx4 v[32:35], v4, s[30:31]
	global_load_dwordx4 v[36:39], v4, s[30:31] offset:1024
	global_load_dwordx4 v[40:43], v4, s[30:31] offset:2048
	global_load_dwordx4 v[44:47], v4, s[30:31] offset:3072
	global_load_dwordx4 v[64:67], v4, s[36:37]
	global_load_dwordx4 v[68:71], v4, s[36:37] offset:1024
	global_load_dwordx4 v[72:75], v4, s[36:37] offset:2048
	global_load_dwordx4 v[76:79], v4, s[36:37] offset:3072
	global_load_dwordx4 v[80:83], v4, s[38:39]
	global_load_dwordx4 v[84:87], v4, s[38:39] offset:1024
	global_load_dwordx4 v[88:91], v4, s[38:39] offset:2048
	global_load_dwordx4 v[92:95], v4, s[38:39] offset:3072
	s_mov_b32 s28, 1
	s_cmp_ge_u32 s28, s23
	s_addc_u32 s44, s28, 0
	s_cmp_ge_u32 s44, s25
	s_addc_u32 s44, s44, 0
	s_lshl_b32 s44, s44, 11
	s_add_i32 s44, s44, s19
	s_mul_hi_u32 s46, s44, 0x38e38e39
	s_lshr_b32 s46, s46, 9
	s_mul_i32 s16, s46, 0x900
	s_sub_u32 s16, s44, s16
	s_cmp_lt_u32 s16, 0x100
	s_cbranch_scc1 .Ln2_2_ctx
	s_lshl_b32 s17, s46, 11
	s_add_i32 s17, s17, s16
	s_add_i32 s17, s17, 0xffffff00
	s_lshl_b32 s17, s17, 12
	s_add_u32 s30, s94, s17
	s_addc_u32 s31, s95, 0
	s_add_i32 s46, s46, s65
	s_branch .Ln2_2_ptr

; DI u32 pack2(float a, float b) { return (u32)f2bf(a) | ((u32)f2bf(b) << 16); }
; DI void phase_norm(const Params& p, int l, int which, int bid, int nblk) {
;     ...
;     float ss = 0.f;
; #pragma unroll
;     for (int i = 0; i < 16; ++i) ss += x[i] * x[i];
;     ss = wave_sum(ss);
;     const float rs = rsqrtf(ss * (1.f / 1024.f) + EPSF);
; #pragma unroll
;     for (int hh = 0; hh < 2; ++hh) {
;       const int c0 = hh * 512 + lane * 8;
;       float y[8];
; #pragma unroll
;       for (int i = 0; i < 8; ++i) {
;         const float yn = x[hh * 8 + i] * rs * g[c0 + i];
;         y[i] = yn * (1.f + mod[1024 + c0 + i]) + mod[c0 + i];
;       }
;       uint4 o = {pack2(y[0], y[1]), pack2(y[2], y[3]), pack2(y[4], y[5]), pack2(y[6], y[7])};
;       *(uint4*)&WSP(u16, OFF_ACT)[(size_t)row * 1024 + c0] = o;
.Ln2_top:
	s_waitcnt vmcnt(16)
	v_mul_f32_e32 v7, v32, v32
	v_fmac_f32_e32 v7, v33, v33
	v_fmac_f32_e32 v7, v34, v34
	v_fmac_f32_e32 v7, v35, v35
	v_fmac_f32_e32 v7, v36, v36
	v_fmac_f32_e32 v7, v37, v37
	v_fmac_f32_e32 v7, v38, v38
	v_fmac_f32_e32 v7, v39, v39
	v_fmac_f32_e32 v7, v40, v40
	v_fmac_f32_e32 v7, v41, v41
	v_fmac_f32_e32 v7, v42, v42
	v_fmac_f32_e32 v7, v43, v43
	v_fmac_f32_e32 v7, v44, v44
	v_fmac_f32_e32 v7, v45, v45
	v_fmac_f32_e32 v7, v46, v46
	v_fmac_f32_e32 v7, v47, v47
	s_nop 1
	v_add_f32_dpp v7, v7, v7 quad_perm:[1,0,3,2] row_mask:0xf bank_mask:0xf
	s_nop 1
	v_add_f32_dpp v7, v7, v7 quad_perm:[2,3,0,1] row_mask:0xf bank_mask:0xf
	s_nop 1
	v_add_f32_dpp v7, v7, v7 row_half_mirror row_mask:0xf bank_mask:0xf
	s_nop 1
	v_add_f32_dpp v7, v7, v7 row_mirror row_mask:0xf bank_mask:0xf
	s_nop 1
	ds_bpermute_b32 v8, v5, v7
	s_waitcnt lgkmcnt(0)
	v_add_f32_e32 v7, v7, v8
	ds_bpermute_b32 v8, v6, v7
	s_waitcnt lgkmcnt(0)
	v_add_f32_e32 v7, v7, v8
	v_mov_b32_e32 v8, 0x358637bd
	v_fmac_f32_e32 v8, 0x3a800000, v7
	v_rsq_f32_e32 v8, v8
	s_nop 0
	v_mul_f32_e32 v32, v32, v8
	v_mul_f32_e32 v33, v33, v8
	v_mul_f32_e32 v34, v34, v8
	v_mul_f32_e32 v35, v35, v8
	v_mul_f32_e32 v36, v36, v8
	v_mul_f32_e32 v37, v37, v8
	v_mul_f32_e32 v38, v38, v8
	v_mul_f32_e32 v39, v39, v8
	v_mul_f32_e32 v40, v40, v8
	v_mul_f32_e32 v41, v41, v8
	v_mul_f32_e32 v42, v42, v8
	v_mul_f32_e32 v43, v43, v8
	v_mul_f32_e32 v44, v44, v8
	v_mul_f32_e32 v45, v45, v8
	v_mul_f32_e32 v46, v46, v8
	v_mul_f32_e32 v47, v47, v8
	v_mul_f32_e32 v32, v32, v16
	v_mul_f32_e32 v33, v33, v17
	v_mul_f32_e32 v34, v34, v18
	v_mul_f32_e32 v35, v35, v19
	v_mul_f32_e32 v36, v36, v20
	v_mul_f32_e32 v37, v37, v21
	v_mul_f32_e32 v38, v38, v22
	v_mul_f32_e32 v39, v39, v23
	v_mul_f32_e32 v40, v40, v24
	v_mul_f32_e32 v41, v41, v25
	v_mul_f32_e32 v42, v42, v26
	v_mul_f32_e32 v43, v43, v27
	v_mul_f32_e32 v44, v44, v28
	v_mul_f32_e32 v45, v45, v29
	v_mul_f32_e32 v46, v46, v30
	v_mul_f32_e32 v47, v47, v31
	v_add_f32_e32 v80, 1.0, v80
	v_add_f32_e32 v81, 1.0, v81
	v_add_f32_e32 v82, 1.0, v82
	v_add_f32_e32 v83, 1.0, v83
	v_add_f32_e32 v84, 1.0, v84
	v_add_f32_e32 v85, 1.0, v85
	v_add_f32_e32 v86, 1.0, v86
	v_add_f32_e32 v87, 1.0, v87
	v_add_f32_e32 v88, 1.0, v88
	v_add_f32_e32 v89, 1.0, v89
	v_add_f32_e32 v90, 1.0, v90
	v_add_f32_e32 v91, 1.0, v91
	v_add_f32_e32 v92, 1.0, v92
	v_add_f32_e32 v93, 1.0, v93
	v_add_f32_e32 v94, 1.0, v94
	v_add_f32_e32 v95, 1.0, v95
	v_fma_f32 v32, v32, v80, v64
	v_fma_f32 v33, v33, v81, v65
	v_fma_f32 v34, v34, v82, v66
	v_fma_f32 v35, v35, v83, v67
	v_fma_f32 v36, v36, v84, v68
	v_fma_f32 v37, v37, v85, v69
	v_fma_f32 v38, v38, v86, v70
	v_fma_f32 v39, v39, v87, v71
	v_fma_f32 v40, v40, v88, v72
	v_fma_f32 v41, v41, v89, v73
	v_fma_f32 v42, v42, v90, v74
	v_fma_f32 v43, v43, v91, v75
	v_fma_f32 v44, v44, v92, v76
	v_fma_f32 v45, v45, v93, v77
	v_fma_f32 v46, v46, v94, v78
	v_fma_f32 v47, v47, v95, v79
	v_cvt_pk_bf16_f32 v32, v32, v33
	v_cvt_pk_bf16_f32 v33, v34, v35
	v_cvt_pk_bf16_f32 v34, v36, v37
	v_cvt_pk_bf16_f32 v35, v38, v39
	v_cvt_pk_bf16_f32 v36, v40, v41
	v_cvt_pk_bf16_f32 v37, v42, v43
	v_cvt_pk_bf16_f32 v38, v44, v45
	v_cvt_pk_bf16_f32 v39, v46, v47
	s_nop 0
	global_store_dwordx2 v9, v[32:33], s[50:51]
	global_store_dwordx2 v9, v[34:35], s[50:51] offset:512
	global_store_dwordx2 v9, v[36:37], s[50:51] offset:1024
	global_store_dwordx2 v9, v[38:39], s[50:51] offset:1536
	s_add_i32 s28, s27, 2
	s_cmp_lt_u32 s28, s26
	s_cselect_b32 s28, s28, 0
	s_cmp_ge_u32 s28, s23
	s_addc_u32 s44, s28, 0
	s_cmp_ge_u32 s44, s25
	s_addc_u32 s44, s44, 0
	s_lshl_b32 s44, s44, 11
	s_add_i32 s44, s44, s19
	s_mul_hi_u32 s46, s44, 0x38e38e39
	s_lshr_b32 s46, s46, 9
	s_mul_i32 s16, s46, 0x900
	s_sub_u32 s16, s44, s16
	s_cmp_lt_u32 s16, 0x100
	s_cbranch_scc1 .Ln2_3_ctx
	s_lshl_b32 s17, s46, 11
	s_add_i32 s17, s17, s16
	s_add_i32 s17, s17, 0xffffff00
	s_lshl_b32 s17, s17, 12
	s_add_u32 s30, s94, s17
	s_addc_u32 s31, s95, 0
	s_add_i32 s46, s46, s65
	s_branch .Ln2_3_ptr

; DI u32 pack2(float a, float b) { return (u32)f2bf(a) | ((u32)f2bf(b) << 16); }
; DI void phase_norm(const Params& p, int l, int which, int bid, int nblk) {
;     ...
;     float ss = 0.f;
; #pragma unroll
;     for (int i = 0; i < 16; ++i) ss += x[i] * x[i];
;     ss = wave_sum(ss);
;     const float rs = rsqrtf(ss * (1.f / 1024.f) + EPSF);
; #pragma unroll
;     for (int hh = 0; hh < 2; ++hh) {
;       const int c0 = hh * 512 + lane * 8;
;       float y[8];
; #pragma unroll
;       for (int i = 0; i < 8; ++i) {
;         const float yn = x[hh * 8 + i] * rs * g[c0 + i];
;         y[i] = yn * (1.f + mod[1024 + c0 + i]) + mod[c0 + i];
;       }
;       uint4 o = {pack2(y[0], y[1]), pack2(y[2], y[3]), pack2(y[4], y[5]), pack2(y[6], y[7])};
;       *(uint4*)&WSP(u16, OFF_ACT)[(size_t)row * 1024 + c0] = o;
.Ln2_3_ptr:
	s_mul_i32 s46, s46, 0x6000
	s_add_u32 s36, s96, 0x1be07000
	s_addc_u32 s37, s97, 0
	s_add_u32 s36, s36, s46
	s_addc_u32 s37, s37, 0
	s_add_u32 s38, s36, 0x1000
	s_addc_u32 s39, s37, 0
	s_lshl_b32 s17, s44, 11
	s_add_u32 s50, s6, s17
	s_addc_u32 s51, s7, 0
	global_load_dwordx4 v[32:35], v4, s[30:31]
	global_load_dwordx4 v[36:39], v4, s[30:31] offset:1024
	global_load_dwordx4 v[40:43], v4, s[30:31] offset:2048
	global_load_dwordx4 v[44:47], v4, s[30:31] offset:3072
	global_load_dwordx4 v[64:67], v4, s[36:37]
	global_load_dwordx4 v[68:71], v4, s[36:37] offset:1024
	global_load_dwordx4 v[72:75], v4, s[36:37] offset:2048
	global_load_dwordx4 v[76:79], v4, s[36:37] offset:3072
	global_load_dwordx4 v[80:83], v4, s[38:39]
	global_load_dwordx4 v[84:87], v4, s[38:39] offset:1024
	global_load_dwordx4 v[88:91], v4, s[38:39] offset:2048
	global_load_dwordx4 v[92:95], v4, s[38:39] offset:3072
	s_waitcnt vmcnt(16)
	v_mul_f32_e32 v7, v48, v48
	v_fmac_f32_e32 v7, v49, v49
	v_fmac_f32_e32 v7, v50, v50
	v_fmac_f32_e32 v7, v51, v51
	v_fmac_f32_e32 v7, v52, v52
	v_fmac_f32_e32 v7, v53, v53
	v_fmac_f32_e32 v7, v54, v54
	v_fmac_f32_e32 v7, v55, v55
	v_fmac_f32_e32 v7, v56, v56
	v_fmac_f32_e32 v7, v57, v57
	v_fmac_f32_e32 v7, v58, v58
	v_fmac_f32_e32 v7, v59, v59
	v_fmac_f32_e32 v7, v60, v60
	v_fmac_f32_e32 v7, v61, v61
	v_fmac_f32_e32 v7, v62, v62
	v_fmac_f32_e32 v7, v63, v63
	s_nop 1
	v_add_f32_dpp v7, v7, v7 quad_perm:[1,0,3,2] row_mask:0xf bank_mask:0xf
	s_nop 1
	v_add_f32_dpp v7, v7, v7 quad_perm:[2,3,0,1] row_mask:0xf bank_mask:0xf
	s_nop 1
	v_add_f32_dpp v7, v7, v7 row_half_mirror row_mask:0xf bank_mask:0xf
	s_nop 1
	v_add_f32_dpp v7, v7, v7 row_mirror row_mask:0xf bank_mask:0xf
	s_nop 1
	ds_bpermute_b32 v8, v5, v7
	s_waitcnt lgkmcnt(0)
	v_add_f32_e32 v7, v7, v8
	ds_bpermute_b32 v8, v6, v7
	s_waitcnt lgkmcnt(0)
	v_add_f32_e32 v7, v7, v8
	v_mov_b32_e32 v8, 0x358637bd
	v_fmac_f32_e32 v8, 0x3a800000, v7
	v_rsq_f32_e32 v8, v8
	s_nop 0
	v_mul_f32_e32 v48, v48, v8
	v_mul_f32_e32 v49, v49, v8
	v_mul_f32_e32 v50, v50, v8
	v_mul_f32_e32 v51, v51, v8
	v_mul_f32_e32 v52, v52, v8
	v_mul_f32_e32 v53, v53, v8
	v_mul_f32_e32 v54, v54, v8
	v_mul_f32_e32 v55, v55, v8
	v_mul_f32_e32 v56, v56, v8
	v_mul_f32_e32 v57, v57, v8
	v_mul_f32_e32 v58, v58, v8
	v_mul_f32_e32 v59, v59, v8
	v_mul_f32_e32 v60, v60, v8
	v_mul_f32_e32 v61, v61, v8
	v_mul_f32_e32 v62, v62, v8
	v_mul_f32_e32 v63, v63, v8
	v_mul_f32_e32 v48, v48, v16
	v_mul_f32_e32 v49, v49, v17
	v_mul_f32_e32 v50, v50, v18
	v_mul_f32_e32 v51, v51, v19
	v_mul_f32_e32 v52, v52, v20
	v_mul_f32_e32 v53, v53, v21
	v_mul_f32_e32 v54, v54, v22
	v_mul_f32_e32 v55, v55, v23
	v_mul_f32_e32 v56, v56, v24
	v_mul_f32_e32 v57, v57, v25
	v_mul_f32_e32 v58, v58, v26
	v_mul_f32_e32 v59, v59, v27
	v_mul_f32_e32 v60, v60, v28
	v_mul_f32_e32 v61, v61, v29
	v_mul_f32_e32 v62, v62, v30
	v_mul_f32_e32 v63, v63, v31
	v_add_f32_e32 v112, 1.0, v112
	v_add_f32_e32 v113, 1.0, v113
	v_add_f32_e32 v114, 1.0, v114
	v_add_f32_e32 v115, 1.0, v115
	v_add_f32_e32 v116, 1.0, v116
	v_add_f32_e32 v117, 1.0, v117
	v_add_f32_e32 v118, 1.0, v118
	v_add_f32_e32 v119, 1.0, v119
	v_add_f32_e32 v120, 1.0, v120
	v_add_f32_e32 v121, 1.0, v121
	v_add_f32_e32 v122, 1.0, v122
	v_add_f32_e32 v123, 1.0, v123
	v_add_f32_e32 v124, 1.0, v124
	v_add_f32_e32 v125, 1.0, v125
	v_add_f32_e32 v126, 1.0, v126
	v_add_f32_e32 v127, 1.0, v127
	v_fma_f32 v48, v48, v112, v96
	v_fma_f32 v49, v49, v113, v97
	v_fma_f32 v50, v50, v114, v98
	v_fma_f32 v51, v51, v115, v99
	v_fma_f32 v52, v52, v116, v100
	v_fma_f32 v53, v53, v117, v101
	v_fma_f32 v54, v54, v118, v102
	v_fma_f32 v55, v55, v119, v103
	v_fma_f32 v56, v56, v120, v104
	v_fma_f32 v57, v57, v121, v105
	v_fma_f32 v58, v58, v122, v106
	v_fma_f32 v59, v59, v123, v107
	v_fma_f32 v60, v60, v124, v108
	v_fma_f32 v61, v61, v125, v109
	v_fma_f32 v62, v62, v126, v110
	v_fma_f32 v63, v63, v127, v111
	v_cvt_pk_bf16_f32 v48, v48, v49
	v_cvt_pk_bf16_f32 v49, v50, v51
	v_cvt_pk_bf16_f32 v50, v52, v53
	v_cvt_pk_bf16_f32 v51, v54, v55
	v_cvt_pk_bf16_f32 v52, v56, v57
	v_cvt_pk_bf16_f32 v53, v58, v59
	v_cvt_pk_bf16_f32 v54, v60, v61
	v_cvt_pk_bf16_f32 v55, v62, v63
	s_nop 0
	global_store_dwordx2 v9, v[48:49], s[56:57]
	global_store_dwordx2 v9, v[50:51], s[56:57] offset:512
	global_store_dwordx2 v9, v[52:53], s[56:57] offset:1024
	global_store_dwordx2 v9, v[54:55], s[56:57] offset:1536
	s_add_i32 s28, s27, 3
	s_cmp_lt_u32 s28, s26
	s_cselect_b32 s28, s28, 0
	s_cmp_ge_u32 s28, s23
	s_addc_u32 s44, s28, 0
	s_cmp_ge_u32 s44, s25
	s_addc_u32 s44, s44, 0
	s_lshl_b32 s44, s44, 11
	s_add_i32 s44, s44, s19
	s_mul_hi_u32 s46, s44, 0x38e38e39
	s_lshr_b32 s46, s46, 9
	s_mul_i32 s16, s46, 0x900
	s_sub_u32 s16, s44, s16
	s_cmp_lt_u32 s16, 0x100
	s_cbranch_scc1 .Ln2_4_ctx
	s_lshl_b32 s17, s46, 11
	s_add_i32 s17, s17, s16
	s_add_i32 s17, s17, 0xffffff00
	s_lshl_b32 s17, s17, 12
	s_add_u32 s30, s94, s17
	s_addc_u32 s31, s95, 0
	s_add_i32 s46, s46, s65
	s_branch .Ln2_4_ptr

; DI void phase_norm(const Params& p, int l, int which, int bid, int nblk) {
;     ...
;   for (int row = bid * 4 + w; row < ROWS; row += nblk * 4) {
;     const int b = row / TPB, pos = row % TPB;
;     if (which == 1 && l == 1 && pos < CTXL) continue;
;     const float* xr = xrow_ptr(p, from_input, b, pos);
;     const float* mod = WSP(const float, OFF_MOD) + (size_t)(l * 17 + (pos < CTXL ? 16 : b)) * 6144 + which * 3072;
;     float x[16];
; #pragma unroll
;     for (int hh = 0; hh < 2; ++hh) {
;       const float4 a = *(const float4*)(xr + hh * 512 + lane * 8);
;       const float4 c = *(const float4*)(xr + hh * 512 + lane * 8 + 4);
;       x[hh * 8 + 0] = a.x; x[hh * 8 + 1] = a.y; x[hh * 8 + 2] = a.z; x[hh * 8 + 3] = a.w;
;       x[hh * 8 + 4] = c.x; x[hh * 8 + 5] = c.y; x[hh * 8 + 6] = c.z; x[hh * 8 + 7] = c.w;
;     }
.Ln2_4_ptr:
	s_mul_i32 s46, s46, 0x6000
	s_add_u32 s36, s96, 0x1be07000
	s_addc_u32 s37, s97, 0
	s_add_u32 s36, s36, s46
	s_addc_u32 s37, s37, 0
	s_add_u32 s38, s36, 0x1000
	s_addc_u32 s39, s37, 0
	s_lshl_b32 s17, s44, 11
	s_add_u32 s56, s6, s17
	s_addc_u32 s57, s7, 0
	global_load_dwordx4 v[48:51], v4, s[30:31]
	global_load_dwordx4 v[52:55], v4, s[30:31] offset:1024
	global_load_dwordx4 v[56:59], v4, s[30:31] offset:2048
	global_load_dwordx4 v[60:63], v4, s[30:31] offset:3072
	global_load_dwordx4 v[96:99], v4, s[36:37]
	global_load_dwordx4 v[100:103], v4, s[36:37] offset:1024
	global_load_dwordx4 v[104:107], v4, s[36:37] offset:2048
	global_load_dwordx4 v[108:111], v4, s[36:37] offset:3072
	global_load_dwordx4 v[112:115], v4, s[38:39]
	global_load_dwordx4 v[116:119], v4, s[38:39] offset:1024
	global_load_dwordx4 v[120:123], v4, s[38:39] offset:2048
	global_load_dwordx4 v[124:127], v4, s[38:39] offset:3072
	s_add_i32 s27, s27, 2
	s_cmp_lt_u32 s27, s26
	s_cbranch_scc1 .Ln2_top
	s_waitcnt vmcnt(0)
